# combined + residual epilogues (P2,P5,P9) with the XB tile loads of rows 0-6 issued up front
# baseline (speedup 1.0000x reference)
; __device__ __forceinline__ unsigned cvt_pk_bf16(float lo, float hi) { unsigned r; asm volatile("v_cvt_pk_bf16_f32 %0, %1, %2" : "=v"(r) : "v"(lo), "v"(hi)); return r; }
; __device__ __forceinline__ float bf_lo(unsigned u) { return __uint_as_float(u << 16); }
; __device__ __forceinline__ float bf_hi(unsigned u) { return __uint_as_float(u & 0xffff0000u); }
;     __device__ __forceinline__ void operator()(const f32x4 (&acc)[2][2][4][2], const Unit& u, int wr, int wc, int fr, int fq) const {
;         const int row0 = u.pm * BM + wr * 64 + fr, col0 = u.pn * BM + wc * 32 + 8 * fq;
; #pragma unroll
;         for (int ai = 0; ai < 2; ++ai)
; #pragma unroll
;             for (int m = 0; m < 4; ++m) { const int row = row0 + ai * HALF + m * 16; bf16_t* rowp = XB + (size_t)row * D + col0; float ss = 0.f;
; #pragma unroll
;                 for (int bj = 0; bj < 2; ++bj) { const u32x4 r = *(const u32x4*)(rowp + bj * HALF);
;                     const f32x4 o0 = (f32x4){bf_lo(r.x), bf_hi(r.x), bf_lo(r.y), bf_hi(r.y)} + acc[ai][bj][m][0] * alpha, o1 = (f32x4){bf_lo(r.z), bf_hi(r.z), bf_lo(r.w), bf_hi(r.w)} + acc[ai][bj][m][1] * alpha;
;                     ss += ((o0[0] * o0[0] + o0[1] * o0[1]) + (o0[2] * o0[2] + o0[3] * o0[3])) + ((o1[0] * o1[0] + o1[1] * o1[1]) + (o1[2] * o1[2] + o1[3] * o1[3]));
;                     u32x4 w; w.x = cvt_pk_bf16(o0[0], o0[1]); w.y = cvt_pk_bf16(o0[2], o0[3]); w.z = cvt_pk_bf16(o1[0], o1[1]); w.w = cvt_pk_bf16(o1[2], o1[3]);
;                     *(u32x4*)(rowp + bj * HALF) = w; }
;                 ss += __shfl_xor(ss, 16); ss += __shfl_xor(ss, 32);
;                 if (fq == 0) part[(size_t)row * NPART + u.pn * 4 + wc] = ss; }
.LBB0_364:
	v_lshl_add_u32 v146, s11, 8, v148
	v_ashrrev_i32_e32 v147, 31, v146
	v_lshl_or_b32 v144, s64, 8, v150
	v_lshlrev_b64 v[156:157], 12, v[146:147]
	v_ashrrev_i32_e32 v145, 31, v144
	v_mov_b32_e32 v226, v146
	v_ashrrev_i32_e32 v227, 31, v226
	v_lshlrev_b64 v[226:227], 12, v[226:227]
	v_lshl_add_u64 v[226:227], s[50:51], 0, v[226:227]
	v_lshl_add_u64 v[226:227], v[144:145], 1, v[226:227]
	global_load_dwordx4 v[168:171], v[226:227], off
	global_load_dwordx4 v[172:175], v[226:227], off offset:256
	v_add_u32_e32 v226, 0x10, v146
	v_ashrrev_i32_e32 v227, 31, v226
	v_lshlrev_b64 v[226:227], 12, v[226:227]
	v_lshl_add_u64 v[226:227], s[50:51], 0, v[226:227]
	v_lshl_add_u64 v[226:227], v[144:145], 1, v[226:227]
	global_load_dwordx4 v[176:179], v[226:227], off
	global_load_dwordx4 v[180:183], v[226:227], off offset:256
	v_add_u32_e32 v226, 0x20, v146
	v_ashrrev_i32_e32 v227, 31, v226
	v_lshlrev_b64 v[226:227], 12, v[226:227]
	v_lshl_add_u64 v[226:227], s[50:51], 0, v[226:227]
	v_lshl_add_u64 v[226:227], v[144:145], 1, v[226:227]
	global_load_dwordx4 v[184:187], v[226:227], off
	global_load_dwordx4 v[188:191], v[226:227], off offset:256
	v_add_u32_e32 v226, 0x30, v146
	v_ashrrev_i32_e32 v227, 31, v226
	v_lshlrev_b64 v[226:227], 12, v[226:227]
	v_lshl_add_u64 v[226:227], s[50:51], 0, v[226:227]
	v_lshl_add_u64 v[226:227], v[144:145], 1, v[226:227]
	global_load_dwordx4 v[192:195], v[226:227], off
	global_load_dwordx4 v[196:199], v[226:227], off offset:256
	v_add_u32_e32 v226, 0x80, v146
	v_ashrrev_i32_e32 v227, 31, v226
	v_lshlrev_b64 v[226:227], 12, v[226:227]
	v_lshl_add_u64 v[226:227], s[50:51], 0, v[226:227]
	v_lshl_add_u64 v[226:227], v[144:145], 1, v[226:227]
	global_load_dwordx4 v[200:203], v[226:227], off
	global_load_dwordx4 v[204:207], v[226:227], off offset:256
	v_add_u32_e32 v226, 0x90, v146
	v_ashrrev_i32_e32 v227, 31, v226
	v_lshlrev_b64 v[226:227], 12, v[226:227]
	v_lshl_add_u64 v[226:227], s[50:51], 0, v[226:227]
	v_lshl_add_u64 v[226:227], v[144:145], 1, v[226:227]
	global_load_dwordx4 v[208:211], v[226:227], off
	global_load_dwordx4 v[212:215], v[226:227], off offset:256
	v_add_u32_e32 v226, 0xa0, v146
	v_ashrrev_i32_e32 v227, 31, v226
	v_lshlrev_b64 v[226:227], 12, v[226:227]
	v_lshl_add_u64 v[226:227], s[50:51], 0, v[226:227]
	v_lshl_add_u64 v[226:227], v[144:145], 1, v[226:227]
	global_load_dwordx4 v[216:219], v[226:227], off
	global_load_dwordx4 v[222:225], v[226:227], off offset:256
	v_lshl_add_u64 v[156:157], s[50:51], 0, v[156:157]
	v_lshl_add_u64 v[160:161], v[144:145], 1, v[156:157]
	v_xor_b32_e32 v155, 32, v154
	s_waitcnt vmcnt(13)
	v_mov_b32_e32 v156, v168
	v_mov_b32_e32 v157, v169
	v_mov_b32_e32 v158, v170
	v_mov_b32_e32 v159, v171
	v_lshlrev_b32_e32 v162, 16, v156
	v_and_b32_e32 v163, 0xffff0000, v156
	v_lshlrev_b32_e32 v156, 16, v157
	v_and_b32_e32 v157, 0xffff0000, v157
	v_lshlrev_b32_e32 v164, 16, v158
	v_and_b32_e32 v165, 0xffff0000, v158
	v_lshlrev_b32_e32 v158, 16, v159
	v_and_b32_e32 v159, 0xffff0000, v159
	v_pk_fma_f32 v[126:127], v[126:127], 0.5, v[156:157] op_sel_hi:[1,0,1]
	v_pk_fma_f32 v[162:163], v[124:125], 0.5, v[162:163] op_sel_hi:[1,0,1]
	v_pk_fma_f32 v[166:167], v[122:123], 0.5, v[158:159] op_sel_hi:[1,0,1]
	v_pk_fma_f32 v[164:165], v[120:121], 0.5, v[164:165] op_sel_hi:[1,0,1]
	v_cvt_pk_bf16_f32 v122, v162, v163
	v_cvt_pk_bf16_f32 v123, v126, v127
	v_mul_f32_e32 v163, v163, v163
	v_cvt_pk_bf16_f32 v124, v164, v165
	v_cvt_pk_bf16_f32 v125, v166, v167
	v_mul_f32_e32 v127, v127, v127
	v_mul_f32_e32 v165, v165, v165
	v_mul_f32_e32 v167, v167, v167
	v_fmac_f32_e32 v163, v162, v162
	v_fmac_f32_e32 v127, v126, v126
	v_fmac_f32_e32 v165, v164, v164
	v_fmac_f32_e32 v167, v166, v166
	v_add_f32_e32 v126, v163, v127
	v_add_f32_e32 v127, v165, v167
	v_add_f32_e32 v164, v126, v127
	v_and_b32_e32 v121, 64, v154
	v_xor_b32_e32 v120, 16, v154
	v_add_u32_e32 v121, 64, v121
	v_cmp_lt_i32_e32 vcc, v120, v121
	global_store_dwordx4 v[160:161], v[122:125], off
	s_waitcnt vmcnt(13)
	v_mov_b32_e32 v156, v172
	v_mov_b32_e32 v157, v173
	v_mov_b32_e32 v158, v174
	v_mov_b32_e32 v159, v175
	v_lshlrev_b32_e32 v126, 16, v156
	v_and_b32_e32 v127, 0xffff0000, v156
	v_lshlrev_b32_e32 v156, 16, v157
	v_and_b32_e32 v157, 0xffff0000, v157
	v_lshlrev_b32_e32 v162, 16, v158
	v_and_b32_e32 v163, 0xffff0000, v158
	v_lshlrev_b32_e32 v158, 16, v159
	v_and_b32_e32 v159, 0xffff0000, v159
	v_pk_fma_f32 v[118:119], v[118:119], 0.5, v[156:157] op_sel_hi:[1,0,1]
	v_pk_fma_f32 v[116:117], v[116:117], 0.5, v[126:127] op_sel_hi:[1,0,1]
	v_pk_fma_f32 v[126:127], v[114:115], 0.5, v[158:159] op_sel_hi:[1,0,1]
	v_pk_fma_f32 v[156:157], v[112:113], 0.5, v[162:163] op_sel_hi:[1,0,1]
	v_mul_f32_e32 v112, v117, v117
	v_mul_f32_e32 v113, v119, v119
	v_mul_f32_e32 v114, v157, v157
	v_mul_f32_e32 v115, v127, v127
	v_fmac_f32_e32 v112, v116, v116
	v_fmac_f32_e32 v113, v118, v118
	v_fmac_f32_e32 v114, v156, v156
	v_fmac_f32_e32 v115, v126, v126
	v_add_f32_e32 v112, v112, v113
	v_add_f32_e32 v113, v114, v115
	v_cndmask_b32_e32 v120, v154, v120, vcc
	v_add_f32_e32 v112, v112, v113
	v_lshlrev_b32_e32 v120, 2, v120
	v_add_f32_e32 v112, v164, v112
	ds_bpermute_b32 v113, v120, v112
	v_cmp_lt_i32_e32 vcc, v155, v121
	v_cvt_pk_bf16_f32 v116, v116, v117
	v_cvt_pk_bf16_f32 v117, v118, v119
	v_cvt_pk_bf16_f32 v118, v156, v157
	s_waitcnt lgkmcnt(0)
	v_add_f32_e32 v112, v112, v113
	v_cvt_pk_bf16_f32 v119, v126, v127
	v_cndmask_b32_e32 v114, v154, v155, vcc
	v_lshlrev_b32_e32 v114, 2, v114
	ds_bpermute_b32 v113, v114, v112
	global_store_dwordx4 v[160:161], v[116:119], off offset:256
	s_and_saveexec_b64 s[42:43], s[2:3]
	s_cbranch_execz .LBB0_366
	s_waitcnt lgkmcnt(0)
	v_add_f32_e32 v115, v112, v113
	s_lshl_b32 s44, s64, 2
	v_lshlrev_b64 v[112:113], 7, v[146:147]
	s_ashr_i32 s45, s44, 31
	v_lshl_add_u64 v[112:113], s[48:49], 0, v[112:113]
	v_lshl_add_u64 v[112:113], s[44:45], 2, v[112:113]
	s_lshl_b32 s44, s70, 2
	s_mov_b32 s45, s21
	v_lshl_add_u64 v[112:113], v[112:113], 0, s[44:45]
	global_store_dword v[112:113], v115, off
; __device__ __forceinline__ unsigned cvt_pk_bf16(float lo, float hi) { unsigned r; asm volatile("v_cvt_pk_bf16_f32 %0, %1, %2" : "=v"(r) : "v"(lo), "v"(hi)); return r; }
; __device__ __forceinline__ float bf_lo(unsigned u) { return __uint_as_float(u << 16); }
; __device__ __forceinline__ float bf_hi(unsigned u) { return __uint_as_float(u & 0xffff0000u); }
;     __device__ __forceinline__ void operator()(const f32x4 (&acc)[2][2][4][2], const Unit& u, int wr, int wc, int fr, int fq) const {
;     ...
;         for (int ai = 0; ai < 2; ++ai)
; #pragma unroll
;             for (int m = 0; m < 4; ++m) { const int row = row0 + ai * HALF + m * 16; bf16_t* rowp = XB + (size_t)row * D + col0; float ss = 0.f;
; #pragma unroll
;                 for (int bj = 0; bj < 2; ++bj) { const u32x4 r = *(const u32x4*)(rowp + bj * HALF);
;                     const f32x4 o0 = (f32x4){bf_lo(r.x), bf_hi(r.x), bf_lo(r.y), bf_hi(r.y)} + acc[ai][bj][m][0] * alpha, o1 = (f32x4){bf_lo(r.z), bf_hi(r.z), bf_lo(r.w), bf_hi(r.w)} + acc[ai][bj][m][1] * alpha;
;                     ss += ((o0[0] * o0[0] + o0[1] * o0[1]) + (o0[2] * o0[2] + o0[3] * o0[3])) + ((o1[0] * o1[0] + o1[1] * o1[1]) + (o1[2] * o1[2] + o1[3] * o1[3]));
;                     u32x4 w; w.x = cvt_pk_bf16(o0[0], o0[1]); w.y = cvt_pk_bf16(o0[2], o0[3]); w.z = cvt_pk_bf16(o1[0], o1[1]); w.w = cvt_pk_bf16(o1[2], o1[3]);
;                     *(u32x4*)(rowp + bj * HALF) = w; }
;                 ss += __shfl_xor(ss, 16); ss += __shfl_xor(ss, 32);
;                 if (fq == 0) part[(size_t)row * NPART + u.pn * 4 + wc] = ss; }
.LBB0_366:
	s_or_b64 exec, exec, s[42:43]
	v_or_b32_e32 v112, 16, v146
	s_waitcnt lgkmcnt(0)
	v_ashrrev_i32_e32 v113, 31, v112
	v_lshlrev_b64 v[116:117], 12, v[112:113]
	v_lshl_add_u64 v[116:117], s[50:51], 0, v[116:117]
	v_lshl_add_u64 v[122:123], v[144:145], 1, v[116:117]
	s_waitcnt vmcnt(13)
	v_mov_b32_e32 v116, v176
	v_mov_b32_e32 v117, v177
	v_mov_b32_e32 v118, v178
	v_mov_b32_e32 v119, v179
	v_lshlrev_b32_e32 v124, 16, v116
	v_and_b32_e32 v125, 0xffff0000, v116
	v_lshlrev_b32_e32 v116, 16, v117
	v_and_b32_e32 v117, 0xffff0000, v117
	v_lshlrev_b32_e32 v126, 16, v118
	v_and_b32_e32 v127, 0xffff0000, v118
	v_lshlrev_b32_e32 v118, 16, v119
	v_and_b32_e32 v119, 0xffff0000, v119
	v_pk_fma_f32 v[116:117], v[110:111], 0.5, v[116:117] op_sel_hi:[1,0,1]
	v_pk_fma_f32 v[124:125], v[108:109], 0.5, v[124:125] op_sel_hi:[1,0,1]
	v_pk_fma_f32 v[118:119], v[106:107], 0.5, v[118:119] op_sel_hi:[1,0,1]
	v_pk_fma_f32 v[126:127], v[104:105], 0.5, v[126:127] op_sel_hi:[1,0,1]
	v_cvt_pk_bf16_f32 v104, v124, v125
	v_cvt_pk_bf16_f32 v105, v116, v117
	v_mul_f32_e32 v115, v125, v125
	v_cvt_pk_bf16_f32 v106, v126, v127
	v_cvt_pk_bf16_f32 v107, v118, v119
	v_mul_f32_e32 v117, v117, v117
	v_mul_f32_e32 v121, v127, v127
	v_mul_f32_e32 v119, v119, v119
	v_fmac_f32_e32 v115, v124, v124
	v_fmac_f32_e32 v117, v116, v116
	v_fmac_f32_e32 v121, v126, v126
	v_fmac_f32_e32 v119, v118, v118
	v_add_f32_e32 v115, v115, v117
	v_add_f32_e32 v116, v121, v119
	v_add_f32_e32 v115, v115, v116
	global_store_dwordx4 v[122:123], v[104:107], off
	s_waitcnt vmcnt(13)
	v_mov_b32_e32 v108, v180
	v_mov_b32_e32 v109, v181
	v_mov_b32_e32 v110, v182
	v_mov_b32_e32 v111, v183
	v_lshlrev_b32_e32 v116, 16, v108
	v_and_b32_e32 v117, 0xffff0000, v108
	v_lshlrev_b32_e32 v108, 16, v109
	v_and_b32_e32 v109, 0xffff0000, v109
	v_lshlrev_b32_e32 v118, 16, v110
	v_and_b32_e32 v119, 0xffff0000, v110
	v_lshlrev_b32_e32 v110, 16, v111
	v_and_b32_e32 v111, 0xffff0000, v111
	v_pk_fma_f32 v[102:103], v[102:103], 0.5, v[108:109] op_sel_hi:[1,0,1]
	v_pk_fma_f32 v[100:101], v[100:101], 0.5, v[116:117] op_sel_hi:[1,0,1]
	v_pk_fma_f32 v[108:109], v[98:99], 0.5, v[110:111] op_sel_hi:[1,0,1]
	v_pk_fma_f32 v[110:111], v[96:97], 0.5, v[118:119] op_sel_hi:[1,0,1]
	v_mul_f32_e32 v96, v101, v101
	v_mul_f32_e32 v97, v103, v103
	v_mul_f32_e32 v98, v111, v111
	v_mul_f32_e32 v99, v109, v109
	v_fmac_f32_e32 v96, v100, v100
	v_fmac_f32_e32 v97, v102, v102
	v_fmac_f32_e32 v98, v110, v110
	v_fmac_f32_e32 v99, v108, v108
	v_add_f32_e32 v96, v96, v97
	v_add_f32_e32 v97, v98, v99
	v_add_f32_e32 v96, v96, v97
	v_add_f32_e32 v96, v115, v96
	ds_bpermute_b32 v97, v120, v96
	v_cvt_pk_bf16_f32 v98, v100, v101
	v_cvt_pk_bf16_f32 v99, v102, v103
	v_cvt_pk_bf16_f32 v100, v110, v111
	v_cvt_pk_bf16_f32 v101, v108, v109
	s_waitcnt lgkmcnt(0)
	v_add_f32_e32 v96, v96, v97
	ds_bpermute_b32 v97, v114, v96
	global_store_dwordx4 v[122:123], v[98:101], off offset:256
	s_and_saveexec_b64 s[42:43], s[2:3]
	s_cbranch_execz .LBB0_368
	s_waitcnt lgkmcnt(0)
	v_add_f32_e32 v98, v96, v97
	s_lshl_b32 s44, s64, 2
	v_lshlrev_b64 v[96:97], 7, v[112:113]
	s_ashr_i32 s45, s44, 31
	v_lshl_add_u64 v[96:97], s[48:49], 0, v[96:97]
	v_lshl_add_u64 v[96:97], s[44:45], 2, v[96:97]
	s_lshl_b32 s44, s70, 2
	s_mov_b32 s45, s21
	v_lshl_add_u64 v[96:97], v[96:97], 0, s[44:45]
	global_store_dword v[96:97], v98, off
.LBB0_368:
	s_or_b64 exec, exec, s[42:43]
	v_or_b32_e32 v96, 32, v146
	s_waitcnt lgkmcnt(0)
	v_ashrrev_i32_e32 v97, 31, v96
	v_lshlrev_b64 v[98:99], 12, v[96:97]
	v_lshl_add_u64 v[98:99], s[50:51], 0, v[98:99]
	v_lshl_add_u64 v[102:103], v[144:145], 1, v[98:99]
	s_waitcnt vmcnt(13)
	v_mov_b32_e32 v98, v184
	v_mov_b32_e32 v99, v185
	v_mov_b32_e32 v100, v186
	v_mov_b32_e32 v101, v187
	v_lshlrev_b32_e32 v104, 16, v98
	v_and_b32_e32 v105, 0xffff0000, v98
	v_lshlrev_b32_e32 v98, 16, v99
	v_and_b32_e32 v99, 0xffff0000, v99
	v_lshlrev_b32_e32 v106, 16, v100
	v_and_b32_e32 v107, 0xffff0000, v100
	v_lshlrev_b32_e32 v100, 16, v101
	v_and_b32_e32 v101, 0xffff0000, v101
	v_pk_fma_f32 v[98:99], v[94:95], 0.5, v[98:99] op_sel_hi:[1,0,1]
	v_pk_fma_f32 v[104:105], v[92:93], 0.5, v[104:105] op_sel_hi:[1,0,1]
	v_pk_fma_f32 v[100:101], v[90:91], 0.5, v[100:101] op_sel_hi:[1,0,1]
	v_pk_fma_f32 v[106:107], v[88:89], 0.5, v[106:107] op_sel_hi:[1,0,1]
	v_cvt_pk_bf16_f32 v88, v104, v105
	v_cvt_pk_bf16_f32 v89, v98, v99
	v_mul_f32_e32 v105, v105, v105
	v_cvt_pk_bf16_f32 v90, v106, v107
	v_cvt_pk_bf16_f32 v91, v100, v101
	v_mul_f32_e32 v99, v99, v99
	v_mul_f32_e32 v107, v107, v107
	v_mul_f32_e32 v101, v101, v101
	v_fmac_f32_e32 v105, v104, v104
	v_fmac_f32_e32 v99, v98, v98
	v_fmac_f32_e32 v107, v106, v106
	v_fmac_f32_e32 v101, v100, v100
	v_add_f32_e32 v98, v105, v99
	v_add_f32_e32 v99, v107, v101
	v_add_f32_e32 v104, v98, v99
	global_store_dwordx4 v[102:103], v[88:91], off
	s_waitcnt vmcnt(13)
	v_mov_b32_e32 v92, v188
	v_mov_b32_e32 v93, v189
	v_mov_b32_e32 v94, v190
	v_mov_b32_e32 v95, v191
	v_lshlrev_b32_e32 v98, 16, v92
	v_and_b32_e32 v99, 0xffff0000, v92
	v_lshlrev_b32_e32 v92, 16, v93
	v_and_b32_e32 v93, 0xffff0000, v93
	v_lshlrev_b32_e32 v100, 16, v94
	v_and_b32_e32 v101, 0xffff0000, v94
	v_lshlrev_b32_e32 v94, 16, v95
	v_and_b32_e32 v95, 0xffff0000, v95
	v_pk_fma_f32 v[86:87], v[86:87], 0.5, v[92:93] op_sel_hi:[1,0,1]
	v_pk_fma_f32 v[84:85], v[84:85], 0.5, v[98:99] op_sel_hi:[1,0,1]
	v_pk_fma_f32 v[92:93], v[82:83], 0.5, v[94:95] op_sel_hi:[1,0,1]
	v_pk_fma_f32 v[94:95], v[80:81], 0.5, v[100:101] op_sel_hi:[1,0,1]
	v_mul_f32_e32 v80, v85, v85
	v_mul_f32_e32 v81, v87, v87
	v_mul_f32_e32 v82, v95, v95
	v_mul_f32_e32 v83, v93, v93
	v_fmac_f32_e32 v80, v84, v84
	v_fmac_f32_e32 v81, v86, v86
	v_fmac_f32_e32 v82, v94, v94
	v_fmac_f32_e32 v83, v92, v92
	v_add_f32_e32 v80, v80, v81
	v_add_f32_e32 v81, v82, v83
	v_add_f32_e32 v80, v80, v81
	v_add_f32_e32 v80, v104, v80
	ds_bpermute_b32 v81, v120, v80
	v_cvt_pk_bf16_f32 v82, v84, v85
	v_cvt_pk_bf16_f32 v83, v86, v87
	v_cvt_pk_bf16_f32 v84, v94, v95
	v_cvt_pk_bf16_f32 v85, v92, v93
	s_waitcnt lgkmcnt(0)
	v_add_f32_e32 v80, v80, v81
	ds_bpermute_b32 v81, v114, v80
	global_store_dwordx4 v[102:103], v[82:85], off offset:256
	s_and_saveexec_b64 s[42:43], s[2:3]
	s_cbranch_execz .LBB0_370
	s_waitcnt lgkmcnt(0)
	v_add_f32_e32 v82, v80, v81
	s_lshl_b32 s44, s64, 2
	v_lshlrev_b64 v[80:81], 7, v[96:97]
	s_ashr_i32 s45, s44, 31
	v_lshl_add_u64 v[80:81], s[48:49], 0, v[80:81]
	v_lshl_add_u64 v[80:81], s[44:45], 2, v[80:81]
	s_lshl_b32 s44, s70, 2
	s_mov_b32 s45, s21
	v_lshl_add_u64 v[80:81], v[80:81], 0, s[44:45]
	global_store_dword v[80:81], v82, off
; __device__ __forceinline__ unsigned cvt_pk_bf16(float lo, float hi) { unsigned r; asm volatile("v_cvt_pk_bf16_f32 %0, %1, %2" : "=v"(r) : "v"(lo), "v"(hi)); return r; }
; __device__ __forceinline__ float bf_lo(unsigned u) { return __uint_as_float(u << 16); }
; __device__ __forceinline__ float bf_hi(unsigned u) { return __uint_as_float(u & 0xffff0000u); }
;     __device__ __forceinline__ void operator()(const f32x4 (&acc)[2][2][4][2], const Unit& u, int wr, int wc, int fr, int fq) const {
;     ...
;         for (int ai = 0; ai < 2; ++ai)
; #pragma unroll
;             for (int m = 0; m < 4; ++m) { const int row = row0 + ai * HALF + m * 16; bf16_t* rowp = XB + (size_t)row * D + col0; float ss = 0.f;
; #pragma unroll
;                 for (int bj = 0; bj < 2; ++bj) { const u32x4 r = *(const u32x4*)(rowp + bj * HALF);
;                     const f32x4 o0 = (f32x4){bf_lo(r.x), bf_hi(r.x), bf_lo(r.y), bf_hi(r.y)} + acc[ai][bj][m][0] * alpha, o1 = (f32x4){bf_lo(r.z), bf_hi(r.z), bf_lo(r.w), bf_hi(r.w)} + acc[ai][bj][m][1] * alpha;
;                     ss += ((o0[0] * o0[0] + o0[1] * o0[1]) + (o0[2] * o0[2] + o0[3] * o0[3])) + ((o1[0] * o1[0] + o1[1] * o1[1]) + (o1[2] * o1[2] + o1[3] * o1[3]));
;                     u32x4 w; w.x = cvt_pk_bf16(o0[0], o0[1]); w.y = cvt_pk_bf16(o0[2], o0[3]); w.z = cvt_pk_bf16(o1[0], o1[1]); w.w = cvt_pk_bf16(o1[2], o1[3]);
;                     *(u32x4*)(rowp + bj * HALF) = w; }
;                 ss += __shfl_xor(ss, 16); ss += __shfl_xor(ss, 32);
;                 if (fq == 0) part[(size_t)row * NPART + u.pn * 4 + wc] = ss; }
.LBB0_370:
	s_or_b64 exec, exec, s[42:43]
	v_or_b32_e32 v80, 48, v146
	s_waitcnt lgkmcnt(0)
	v_ashrrev_i32_e32 v81, 31, v80
	v_lshlrev_b64 v[82:83], 12, v[80:81]
	v_lshl_add_u64 v[82:83], s[50:51], 0, v[82:83]
	v_lshl_add_u64 v[86:87], v[144:145], 1, v[82:83]
	s_waitcnt vmcnt(13)
	v_mov_b32_e32 v82, v192
	v_mov_b32_e32 v83, v193
	v_mov_b32_e32 v84, v194
	v_mov_b32_e32 v85, v195
	v_lshlrev_b32_e32 v88, 16, v82
	v_and_b32_e32 v89, 0xffff0000, v82
	v_lshlrev_b32_e32 v82, 16, v83
	v_and_b32_e32 v83, 0xffff0000, v83
	v_lshlrev_b32_e32 v90, 16, v84
	v_and_b32_e32 v91, 0xffff0000, v84
	v_lshlrev_b32_e32 v84, 16, v85
	v_and_b32_e32 v85, 0xffff0000, v85
	v_pk_fma_f32 v[82:83], v[78:79], 0.5, v[82:83] op_sel_hi:[1,0,1]
	v_pk_fma_f32 v[88:89], v[76:77], 0.5, v[88:89] op_sel_hi:[1,0,1]
	v_pk_fma_f32 v[84:85], v[74:75], 0.5, v[84:85] op_sel_hi:[1,0,1]
	v_pk_fma_f32 v[90:91], v[72:73], 0.5, v[90:91] op_sel_hi:[1,0,1]
	v_cvt_pk_bf16_f32 v72, v88, v89
	v_cvt_pk_bf16_f32 v73, v82, v83
	v_mul_f32_e32 v89, v89, v89
	v_cvt_pk_bf16_f32 v74, v90, v91
	v_cvt_pk_bf16_f32 v75, v84, v85
	v_mul_f32_e32 v83, v83, v83
	v_mul_f32_e32 v91, v91, v91
	v_mul_f32_e32 v85, v85, v85
	v_fmac_f32_e32 v89, v88, v88
	v_fmac_f32_e32 v83, v82, v82
	v_fmac_f32_e32 v91, v90, v90
	v_fmac_f32_e32 v85, v84, v84
	v_add_f32_e32 v82, v89, v83
	v_add_f32_e32 v83, v91, v85
	v_add_f32_e32 v88, v82, v83
	global_store_dwordx4 v[86:87], v[72:75], off
	s_waitcnt vmcnt(13)
	v_mov_b32_e32 v76, v196
	v_mov_b32_e32 v77, v197
	v_mov_b32_e32 v78, v198
	v_mov_b32_e32 v79, v199
	v_lshlrev_b32_e32 v82, 16, v76
	v_and_b32_e32 v83, 0xffff0000, v76
	v_lshlrev_b32_e32 v76, 16, v77
	v_and_b32_e32 v77, 0xffff0000, v77
	v_lshlrev_b32_e32 v84, 16, v78
	v_and_b32_e32 v85, 0xffff0000, v78
	v_lshlrev_b32_e32 v78, 16, v79
	v_and_b32_e32 v79, 0xffff0000, v79
	v_pk_fma_f32 v[70:71], v[70:71], 0.5, v[76:77] op_sel_hi:[1,0,1]
	v_pk_fma_f32 v[68:69], v[68:69], 0.5, v[82:83] op_sel_hi:[1,0,1]
	v_pk_fma_f32 v[76:77], v[66:67], 0.5, v[78:79] op_sel_hi:[1,0,1]
	v_pk_fma_f32 v[78:79], v[64:65], 0.5, v[84:85] op_sel_hi:[1,0,1]
	v_mul_f32_e32 v64, v69, v69
	v_mul_f32_e32 v65, v71, v71
	v_mul_f32_e32 v66, v79, v79
	v_mul_f32_e32 v67, v77, v77
	v_fmac_f32_e32 v64, v68, v68
	v_fmac_f32_e32 v65, v70, v70
	v_fmac_f32_e32 v66, v78, v78
	v_fmac_f32_e32 v67, v76, v76
	v_add_f32_e32 v64, v64, v65
	v_add_f32_e32 v65, v66, v67
	v_add_f32_e32 v64, v64, v65
	v_add_f32_e32 v64, v88, v64
	ds_bpermute_b32 v65, v120, v64
	v_cvt_pk_bf16_f32 v66, v68, v69
	v_cvt_pk_bf16_f32 v67, v70, v71
	v_cvt_pk_bf16_f32 v68, v78, v79
	v_cvt_pk_bf16_f32 v69, v76, v77
	s_waitcnt lgkmcnt(0)
	v_add_f32_e32 v64, v64, v65
	ds_bpermute_b32 v65, v114, v64
	global_store_dwordx4 v[86:87], v[66:69], off offset:256
	s_and_saveexec_b64 s[42:43], s[2:3]
	s_cbranch_execz .LBB0_372
	s_waitcnt lgkmcnt(0)
	v_add_f32_e32 v66, v64, v65
	s_lshl_b32 s44, s64, 2
	v_lshlrev_b64 v[64:65], 7, v[80:81]
	s_ashr_i32 s45, s44, 31
	v_lshl_add_u64 v[64:65], s[48:49], 0, v[64:65]
	v_lshl_add_u64 v[64:65], s[44:45], 2, v[64:65]
	s_lshl_b32 s44, s70, 2
	s_mov_b32 s45, s21
	v_lshl_add_u64 v[64:65], v[64:65], 0, s[44:45]
	global_store_dword v[64:65], v66, off
.LBB0_372:
	s_or_b64 exec, exec, s[42:43]
	v_add_u32_e32 v64, 0x80, v146
	s_waitcnt lgkmcnt(0)
	v_ashrrev_i32_e32 v65, 31, v64
	v_lshlrev_b64 v[66:67], 12, v[64:65]
	v_lshl_add_u64 v[66:67], s[50:51], 0, v[66:67]
	v_lshl_add_u64 v[70:71], v[144:145], 1, v[66:67]
	s_waitcnt vmcnt(13)
	v_mov_b32_e32 v66, v200
	v_mov_b32_e32 v67, v201
	v_mov_b32_e32 v68, v202
	v_mov_b32_e32 v69, v203
	v_lshlrev_b32_e32 v72, 16, v66
	v_and_b32_e32 v73, 0xffff0000, v66
	v_lshlrev_b32_e32 v66, 16, v67
	v_and_b32_e32 v67, 0xffff0000, v67
	v_lshlrev_b32_e32 v74, 16, v68
	v_and_b32_e32 v75, 0xffff0000, v68
	v_lshlrev_b32_e32 v68, 16, v69
	v_and_b32_e32 v69, 0xffff0000, v69
	v_pk_fma_f32 v[66:67], v[62:63], 0.5, v[66:67] op_sel_hi:[1,0,1]
	v_pk_fma_f32 v[72:73], v[60:61], 0.5, v[72:73] op_sel_hi:[1,0,1]
	v_pk_fma_f32 v[68:69], v[58:59], 0.5, v[68:69] op_sel_hi:[1,0,1]
	v_pk_fma_f32 v[74:75], v[56:57], 0.5, v[74:75] op_sel_hi:[1,0,1]
	v_cvt_pk_bf16_f32 v56, v72, v73
	v_cvt_pk_bf16_f32 v57, v66, v67
	v_mul_f32_e32 v73, v73, v73
	v_cvt_pk_bf16_f32 v58, v74, v75
	v_cvt_pk_bf16_f32 v59, v68, v69
	v_mul_f32_e32 v67, v67, v67
	v_mul_f32_e32 v75, v75, v75
	v_mul_f32_e32 v69, v69, v69
	v_fmac_f32_e32 v73, v72, v72
	v_fmac_f32_e32 v67, v66, v66
	v_fmac_f32_e32 v75, v74, v74
	v_fmac_f32_e32 v69, v68, v68
	v_add_f32_e32 v66, v73, v67
	v_add_f32_e32 v67, v75, v69
	v_add_f32_e32 v72, v66, v67
	global_store_dwordx4 v[70:71], v[56:59], off
	s_waitcnt vmcnt(13)
	v_mov_b32_e32 v60, v204
	v_mov_b32_e32 v61, v205
	v_mov_b32_e32 v62, v206
	v_mov_b32_e32 v63, v207
	v_lshlrev_b32_e32 v66, 16, v60
	v_and_b32_e32 v67, 0xffff0000, v60
	v_lshlrev_b32_e32 v60, 16, v61
	v_and_b32_e32 v61, 0xffff0000, v61
	v_lshlrev_b32_e32 v68, 16, v62
	v_and_b32_e32 v69, 0xffff0000, v62
	v_lshlrev_b32_e32 v62, 16, v63
	v_and_b32_e32 v63, 0xffff0000, v63
	v_pk_fma_f32 v[54:55], v[54:55], 0.5, v[60:61] op_sel_hi:[1,0,1]
	v_pk_fma_f32 v[52:53], v[52:53], 0.5, v[66:67] op_sel_hi:[1,0,1]
	v_pk_fma_f32 v[60:61], v[50:51], 0.5, v[62:63] op_sel_hi:[1,0,1]
	v_pk_fma_f32 v[62:63], v[48:49], 0.5, v[68:69] op_sel_hi:[1,0,1]
	v_mul_f32_e32 v48, v53, v53
	v_mul_f32_e32 v49, v55, v55
	v_mul_f32_e32 v50, v63, v63
	v_mul_f32_e32 v51, v61, v61
	v_fmac_f32_e32 v48, v52, v52
	v_fmac_f32_e32 v49, v54, v54
	v_fmac_f32_e32 v50, v62, v62
	v_fmac_f32_e32 v51, v60, v60
	v_add_f32_e32 v48, v48, v49
	v_add_f32_e32 v49, v50, v51
	v_add_f32_e32 v48, v48, v49
	v_add_f32_e32 v48, v72, v48
	ds_bpermute_b32 v49, v120, v48
	v_cvt_pk_bf16_f32 v50, v52, v53
	v_cvt_pk_bf16_f32 v51, v54, v55
	v_cvt_pk_bf16_f32 v52, v62, v63
	v_cvt_pk_bf16_f32 v53, v60, v61
	s_waitcnt lgkmcnt(0)
	v_add_f32_e32 v48, v48, v49
	ds_bpermute_b32 v49, v114, v48
	global_store_dwordx4 v[70:71], v[50:53], off offset:256
	s_and_saveexec_b64 s[42:43], s[2:3]
	s_cbranch_execz .LBB0_374
	s_waitcnt lgkmcnt(0)
	v_add_f32_e32 v50, v48, v49
	s_lshl_b32 s44, s64, 2
	v_lshlrev_b64 v[48:49], 7, v[64:65]
	s_ashr_i32 s45, s44, 31
	v_lshl_add_u64 v[48:49], s[48:49], 0, v[48:49]
	v_lshl_add_u64 v[48:49], s[44:45], 2, v[48:49]
	s_lshl_b32 s44, s70, 2
	s_mov_b32 s45, s21
	v_lshl_add_u64 v[48:49], v[48:49], 0, s[44:45]
	global_store_dword v[48:49], v50, off
; __device__ __forceinline__ unsigned cvt_pk_bf16(float lo, float hi) { unsigned r; asm volatile("v_cvt_pk_bf16_f32 %0, %1, %2" : "=v"(r) : "v"(lo), "v"(hi)); return r; }
; __device__ __forceinline__ float bf_lo(unsigned u) { return __uint_as_float(u << 16); }
; __device__ __forceinline__ float bf_hi(unsigned u) { return __uint_as_float(u & 0xffff0000u); }
;     __device__ __forceinline__ void operator()(const f32x4 (&acc)[2][2][4][2], const Unit& u, int wr, int wc, int fr, int fq) const {
;     ...
;         for (int ai = 0; ai < 2; ++ai)
; #pragma unroll
;             for (int m = 0; m < 4; ++m) { const int row = row0 + ai * HALF + m * 16; bf16_t* rowp = XB + (size_t)row * D + col0; float ss = 0.f;
; #pragma unroll
;                 for (int bj = 0; bj < 2; ++bj) { const u32x4 r = *(const u32x4*)(rowp + bj * HALF);
;                     const f32x4 o0 = (f32x4){bf_lo(r.x), bf_hi(r.x), bf_lo(r.y), bf_hi(r.y)} + acc[ai][bj][m][0] * alpha, o1 = (f32x4){bf_lo(r.z), bf_hi(r.z), bf_lo(r.w), bf_hi(r.w)} + acc[ai][bj][m][1] * alpha;
;                     ss += ((o0[0] * o0[0] + o0[1] * o0[1]) + (o0[2] * o0[2] + o0[3] * o0[3])) + ((o1[0] * o1[0] + o1[1] * o1[1]) + (o1[2] * o1[2] + o1[3] * o1[3]));
;                     u32x4 w; w.x = cvt_pk_bf16(o0[0], o0[1]); w.y = cvt_pk_bf16(o0[2], o0[3]); w.z = cvt_pk_bf16(o1[0], o1[1]); w.w = cvt_pk_bf16(o1[2], o1[3]);
;                     *(u32x4*)(rowp + bj * HALF) = w; }
;                 ss += __shfl_xor(ss, 16); ss += __shfl_xor(ss, 32);
;                 if (fq == 0) part[(size_t)row * NPART + u.pn * 4 + wc] = ss; }
.LBB0_374:
	s_or_b64 exec, exec, s[42:43]
	v_add_u32_e32 v48, 0x90, v146
	s_waitcnt lgkmcnt(0)
	v_ashrrev_i32_e32 v49, 31, v48
	v_lshlrev_b64 v[50:51], 12, v[48:49]
	v_lshl_add_u64 v[50:51], s[50:51], 0, v[50:51]
	v_lshl_add_u64 v[54:55], v[144:145], 1, v[50:51]
	s_waitcnt vmcnt(13)
	v_mov_b32_e32 v50, v208
	v_mov_b32_e32 v51, v209
	v_mov_b32_e32 v52, v210
	v_mov_b32_e32 v53, v211
	v_lshlrev_b32_e32 v56, 16, v50
	v_and_b32_e32 v57, 0xffff0000, v50
	v_lshlrev_b32_e32 v50, 16, v51
	v_and_b32_e32 v51, 0xffff0000, v51
	v_lshlrev_b32_e32 v58, 16, v52
	v_and_b32_e32 v59, 0xffff0000, v52
	v_lshlrev_b32_e32 v52, 16, v53
	v_and_b32_e32 v53, 0xffff0000, v53
	v_pk_fma_f32 v[50:51], v[46:47], 0.5, v[50:51] op_sel_hi:[1,0,1]
	v_pk_fma_f32 v[56:57], v[44:45], 0.5, v[56:57] op_sel_hi:[1,0,1]
	v_pk_fma_f32 v[52:53], v[42:43], 0.5, v[52:53] op_sel_hi:[1,0,1]
	v_pk_fma_f32 v[58:59], v[40:41], 0.5, v[58:59] op_sel_hi:[1,0,1]
	v_cvt_pk_bf16_f32 v40, v56, v57
	v_cvt_pk_bf16_f32 v41, v50, v51
	v_mul_f32_e32 v57, v57, v57
	v_cvt_pk_bf16_f32 v42, v58, v59
	v_cvt_pk_bf16_f32 v43, v52, v53
	v_mul_f32_e32 v51, v51, v51
	v_mul_f32_e32 v59, v59, v59
	v_mul_f32_e32 v53, v53, v53
	v_fmac_f32_e32 v57, v56, v56
	v_fmac_f32_e32 v51, v50, v50
	v_fmac_f32_e32 v59, v58, v58
	v_fmac_f32_e32 v53, v52, v52
	v_add_f32_e32 v50, v57, v51
	v_add_f32_e32 v51, v59, v53
	v_add_f32_e32 v56, v50, v51
	global_store_dwordx4 v[54:55], v[40:43], off
	s_waitcnt vmcnt(13)
	v_mov_b32_e32 v44, v212
	v_mov_b32_e32 v45, v213
	v_mov_b32_e32 v46, v214
	v_mov_b32_e32 v47, v215
	v_lshlrev_b32_e32 v50, 16, v44
	v_and_b32_e32 v51, 0xffff0000, v44
	v_lshlrev_b32_e32 v44, 16, v45
	v_and_b32_e32 v45, 0xffff0000, v45
	v_lshlrev_b32_e32 v52, 16, v46
	v_and_b32_e32 v53, 0xffff0000, v46
	v_lshlrev_b32_e32 v46, 16, v47
	v_and_b32_e32 v47, 0xffff0000, v47
	v_pk_fma_f32 v[38:39], v[38:39], 0.5, v[44:45] op_sel_hi:[1,0,1]
	v_pk_fma_f32 v[36:37], v[36:37], 0.5, v[50:51] op_sel_hi:[1,0,1]
	v_pk_fma_f32 v[44:45], v[34:35], 0.5, v[46:47] op_sel_hi:[1,0,1]
	v_pk_fma_f32 v[46:47], v[32:33], 0.5, v[52:53] op_sel_hi:[1,0,1]
	v_mul_f32_e32 v32, v37, v37
	v_mul_f32_e32 v33, v39, v39
	v_mul_f32_e32 v34, v47, v47
	v_mul_f32_e32 v35, v45, v45
	v_fmac_f32_e32 v32, v36, v36
	v_fmac_f32_e32 v33, v38, v38
	v_fmac_f32_e32 v34, v46, v46
	v_fmac_f32_e32 v35, v44, v44
	v_add_f32_e32 v32, v32, v33
	v_add_f32_e32 v33, v34, v35
	v_add_f32_e32 v32, v32, v33
	v_add_f32_e32 v32, v56, v32
	ds_bpermute_b32 v33, v120, v32
	v_cvt_pk_bf16_f32 v34, v36, v37
	v_cvt_pk_bf16_f32 v35, v38, v39
	v_cvt_pk_bf16_f32 v36, v46, v47
	v_cvt_pk_bf16_f32 v37, v44, v45
	s_waitcnt lgkmcnt(0)
	v_add_f32_e32 v32, v32, v33
	ds_bpermute_b32 v33, v114, v32
	global_store_dwordx4 v[54:55], v[34:37], off offset:256
	s_and_saveexec_b64 s[42:43], s[2:3]
	s_cbranch_execz .LBB0_376
	s_waitcnt lgkmcnt(0)
	v_add_f32_e32 v34, v32, v33
	s_lshl_b32 s44, s64, 2
	v_lshlrev_b64 v[32:33], 7, v[48:49]
	s_ashr_i32 s45, s44, 31
	v_lshl_add_u64 v[32:33], s[48:49], 0, v[32:33]
	v_lshl_add_u64 v[32:33], s[44:45], 2, v[32:33]
	s_lshl_b32 s44, s70, 2
	s_mov_b32 s45, s21
	v_lshl_add_u64 v[32:33], v[32:33], 0, s[44:45]
	global_store_dword v[32:33], v34, off
.LBB0_376:
	s_or_b64 exec, exec, s[42:43]
	v_add_u32_e32 v32, 0xa0, v146
	s_waitcnt lgkmcnt(0)
	v_ashrrev_i32_e32 v33, 31, v32
	v_lshlrev_b64 v[34:35], 12, v[32:33]
	v_lshl_add_u64 v[34:35], s[50:51], 0, v[34:35]
	v_lshl_add_u64 v[38:39], v[144:145], 1, v[34:35]
	s_waitcnt vmcnt(13)
	v_mov_b32_e32 v34, v216
	v_mov_b32_e32 v35, v217
	v_mov_b32_e32 v36, v218
	v_mov_b32_e32 v37, v219
	v_lshlrev_b32_e32 v40, 16, v34
	v_and_b32_e32 v41, 0xffff0000, v34
	v_lshlrev_b32_e32 v34, 16, v35
	v_and_b32_e32 v35, 0xffff0000, v35
	v_lshlrev_b32_e32 v42, 16, v36
	v_and_b32_e32 v43, 0xffff0000, v36
	v_lshlrev_b32_e32 v36, 16, v37
	v_and_b32_e32 v37, 0xffff0000, v37
	v_pk_fma_f32 v[34:35], v[30:31], 0.5, v[34:35] op_sel_hi:[1,0,1]
	v_pk_fma_f32 v[40:41], v[28:29], 0.5, v[40:41] op_sel_hi:[1,0,1]
	v_pk_fma_f32 v[36:37], v[26:27], 0.5, v[36:37] op_sel_hi:[1,0,1]
	v_pk_fma_f32 v[42:43], v[24:25], 0.5, v[42:43] op_sel_hi:[1,0,1]
	v_cvt_pk_bf16_f32 v24, v40, v41
	v_cvt_pk_bf16_f32 v25, v34, v35
	v_mul_f32_e32 v41, v41, v41
	v_cvt_pk_bf16_f32 v26, v42, v43
	v_cvt_pk_bf16_f32 v27, v36, v37
	v_mul_f32_e32 v35, v35, v35
	v_mul_f32_e32 v43, v43, v43
	v_mul_f32_e32 v37, v37, v37
	v_fmac_f32_e32 v41, v40, v40
	v_fmac_f32_e32 v35, v34, v34
	v_fmac_f32_e32 v43, v42, v42
	v_fmac_f32_e32 v37, v36, v36
	v_add_f32_e32 v34, v41, v35
	v_add_f32_e32 v35, v43, v37
	v_add_f32_e32 v40, v34, v35
	global_store_dwordx4 v[38:39], v[24:27], off
	s_waitcnt vmcnt(13)
	v_mov_b32_e32 v28, v222
	v_mov_b32_e32 v29, v223
	v_mov_b32_e32 v30, v224
	v_mov_b32_e32 v31, v225
	v_lshlrev_b32_e32 v34, 16, v28
	v_and_b32_e32 v35, 0xffff0000, v28
	v_lshlrev_b32_e32 v28, 16, v29
	v_and_b32_e32 v29, 0xffff0000, v29
	v_lshlrev_b32_e32 v36, 16, v30
	v_and_b32_e32 v37, 0xffff0000, v30
	v_lshlrev_b32_e32 v30, 16, v31
	v_and_b32_e32 v31, 0xffff0000, v31
	v_pk_fma_f32 v[22:23], v[22:23], 0.5, v[28:29] op_sel_hi:[1,0,1]
	v_pk_fma_f32 v[20:21], v[20:21], 0.5, v[34:35] op_sel_hi:[1,0,1]
	v_pk_fma_f32 v[28:29], v[18:19], 0.5, v[30:31] op_sel_hi:[1,0,1]
	v_pk_fma_f32 v[30:31], v[16:17], 0.5, v[36:37] op_sel_hi:[1,0,1]
	v_mul_f32_e32 v16, v21, v21
	v_mul_f32_e32 v17, v23, v23
	v_mul_f32_e32 v18, v31, v31
	v_mul_f32_e32 v19, v29, v29
	v_fmac_f32_e32 v16, v20, v20
	v_fmac_f32_e32 v17, v22, v22
	v_fmac_f32_e32 v18, v30, v30
	v_fmac_f32_e32 v19, v28, v28
	v_add_f32_e32 v16, v16, v17
	v_add_f32_e32 v17, v18, v19
	v_add_f32_e32 v16, v16, v17
	v_add_f32_e32 v16, v40, v16
	ds_bpermute_b32 v17, v120, v16
	v_cvt_pk_bf16_f32 v18, v20, v21
	v_cvt_pk_bf16_f32 v19, v22, v23
	v_cvt_pk_bf16_f32 v20, v30, v31
	v_cvt_pk_bf16_f32 v21, v28, v29
	s_waitcnt lgkmcnt(0)
	v_add_f32_e32 v16, v16, v17
	ds_bpermute_b32 v17, v114, v16
	global_store_dwordx4 v[38:39], v[18:21], off offset:256
	s_and_saveexec_b64 s[42:43], s[2:3]
	s_cbranch_execz .LBB0_378
	s_waitcnt lgkmcnt(0)
	v_add_f32_e32 v18, v16, v17
	s_lshl_b32 s44, s64, 2
	v_lshlrev_b64 v[16:17], 7, v[32:33]
	s_ashr_i32 s45, s44, 31
	v_lshl_add_u64 v[16:17], s[48:49], 0, v[16:17]
	v_lshl_add_u64 v[16:17], s[44:45], 2, v[16:17]
	s_lshl_b32 s44, s70, 2
	s_mov_b32 s45, s21
	v_lshl_add_u64 v[16:17], v[16:17], 0, s[44:45]
	global_store_dword v[16:17], v18, off

; __device__ __forceinline__ unsigned cvt_pk_bf16(float lo, float hi) { unsigned r; asm volatile("v_cvt_pk_bf16_f32 %0, %1, %2" : "=v"(r) : "v"(lo), "v"(hi)); return r; }
; __device__ __forceinline__ float bf_lo(unsigned u) { return __uint_as_float(u << 16); }
; __device__ __forceinline__ float bf_hi(unsigned u) { return __uint_as_float(u & 0xffff0000u); }
;     __device__ __forceinline__ void operator()(const f32x4 (&acc)[2][2][4][2], const Unit& u, int wr, int wc, int fr, int fq) const {
;         const int row0 = u.pm * BM + wr * 64 + fr, col0 = u.pn * BM + wc * 32 + 8 * fq;
; #pragma unroll
;         for (int ai = 0; ai < 2; ++ai)
; #pragma unroll
;             for (int m = 0; m < 4; ++m) { const int row = row0 + ai * HALF + m * 16; bf16_t* rowp = XB + (size_t)row * D + col0; float ss = 0.f;
; #pragma unroll
;                 for (int bj = 0; bj < 2; ++bj) { const u32x4 r = *(const u32x4*)(rowp + bj * HALF);
;                     const f32x4 o0 = (f32x4){bf_lo(r.x), bf_hi(r.x), bf_lo(r.y), bf_hi(r.y)} + acc[ai][bj][m][0] * alpha, o1 = (f32x4){bf_lo(r.z), bf_hi(r.z), bf_lo(r.w), bf_hi(r.w)} + acc[ai][bj][m][1] * alpha;
;                     ss += ((o0[0] * o0[0] + o0[1] * o0[1]) + (o0[2] * o0[2] + o0[3] * o0[3])) + ((o1[0] * o1[0] + o1[1] * o1[1]) + (o1[2] * o1[2] + o1[3] * o1[3]));
;                     u32x4 w; w.x = cvt_pk_bf16(o0[0], o0[1]); w.y = cvt_pk_bf16(o0[2], o0[3]); w.z = cvt_pk_bf16(o1[0], o1[1]); w.w = cvt_pk_bf16(o1[2], o1[3]);
;                     *(u32x4*)(rowp + bj * HALF) = w; }
;                 ss += __shfl_xor(ss, 16); ss += __shfl_xor(ss, 32);
;                 if (fq == 0) part[(size_t)row * NPART + u.pn * 4 + wc] = ss; }
.LBB0_848:
	v_lshl_add_u32 v146, s11, 8, v148
	v_ashrrev_i32_e32 v147, 31, v146
	v_lshl_or_b32 v144, s64, 8, v150
	v_lshlrev_b64 v[156:157], 12, v[146:147]
	v_ashrrev_i32_e32 v145, 31, v144
	v_mov_b32_e32 v226, v146
	v_ashrrev_i32_e32 v227, 31, v226
	v_lshlrev_b64 v[226:227], 12, v[226:227]
	v_lshl_add_u64 v[226:227], s[50:51], 0, v[226:227]
	v_lshl_add_u64 v[226:227], v[144:145], 1, v[226:227]
	global_load_dwordx4 v[168:171], v[226:227], off
	global_load_dwordx4 v[172:175], v[226:227], off offset:256
	v_add_u32_e32 v226, 0x10, v146
	v_ashrrev_i32_e32 v227, 31, v226
	v_lshlrev_b64 v[226:227], 12, v[226:227]
	v_lshl_add_u64 v[226:227], s[50:51], 0, v[226:227]
	v_lshl_add_u64 v[226:227], v[144:145], 1, v[226:227]
	global_load_dwordx4 v[176:179], v[226:227], off
	global_load_dwordx4 v[180:183], v[226:227], off offset:256
	v_add_u32_e32 v226, 0x20, v146
	v_ashrrev_i32_e32 v227, 31, v226
	v_lshlrev_b64 v[226:227], 12, v[226:227]
	v_lshl_add_u64 v[226:227], s[50:51], 0, v[226:227]
	v_lshl_add_u64 v[226:227], v[144:145], 1, v[226:227]
	global_load_dwordx4 v[184:187], v[226:227], off
	global_load_dwordx4 v[188:191], v[226:227], off offset:256
	v_add_u32_e32 v226, 0x30, v146
	v_ashrrev_i32_e32 v227, 31, v226
	v_lshlrev_b64 v[226:227], 12, v[226:227]
	v_lshl_add_u64 v[226:227], s[50:51], 0, v[226:227]
	v_lshl_add_u64 v[226:227], v[144:145], 1, v[226:227]
	global_load_dwordx4 v[192:195], v[226:227], off
	global_load_dwordx4 v[196:199], v[226:227], off offset:256
	v_add_u32_e32 v226, 0x80, v146
	v_ashrrev_i32_e32 v227, 31, v226
	v_lshlrev_b64 v[226:227], 12, v[226:227]
	v_lshl_add_u64 v[226:227], s[50:51], 0, v[226:227]
	v_lshl_add_u64 v[226:227], v[144:145], 1, v[226:227]
	global_load_dwordx4 v[200:203], v[226:227], off
	global_load_dwordx4 v[204:207], v[226:227], off offset:256
	v_add_u32_e32 v226, 0x90, v146
	v_ashrrev_i32_e32 v227, 31, v226
	v_lshlrev_b64 v[226:227], 12, v[226:227]
	v_lshl_add_u64 v[226:227], s[50:51], 0, v[226:227]
	v_lshl_add_u64 v[226:227], v[144:145], 1, v[226:227]
	global_load_dwordx4 v[208:211], v[226:227], off
	global_load_dwordx4 v[212:215], v[226:227], off offset:256
	v_add_u32_e32 v226, 0xa0, v146
	v_ashrrev_i32_e32 v227, 31, v226
	v_lshlrev_b64 v[226:227], 12, v[226:227]
	v_lshl_add_u64 v[226:227], s[50:51], 0, v[226:227]
	v_lshl_add_u64 v[226:227], v[144:145], 1, v[226:227]
	global_load_dwordx4 v[216:219], v[226:227], off
	global_load_dwordx4 v[222:225], v[226:227], off offset:256
	v_lshl_add_u64 v[156:157], s[50:51], 0, v[156:157]
	v_lshl_add_u64 v[160:161], v[144:145], 1, v[156:157]
	v_xor_b32_e32 v155, 32, v154
	s_waitcnt vmcnt(13)
	v_mov_b32_e32 v156, v168
	v_mov_b32_e32 v157, v169
	v_mov_b32_e32 v158, v170
	v_mov_b32_e32 v159, v171
	v_lshlrev_b32_e32 v162, 16, v156
	v_and_b32_e32 v163, 0xffff0000, v156
	v_lshlrev_b32_e32 v156, 16, v157
	v_and_b32_e32 v157, 0xffff0000, v157
	v_lshlrev_b32_e32 v164, 16, v158
	v_and_b32_e32 v165, 0xffff0000, v158
	v_lshlrev_b32_e32 v158, 16, v159
	v_and_b32_e32 v159, 0xffff0000, v159
	v_pk_add_f32 v[126:127], v[126:127], v[156:157]
	v_pk_add_f32 v[162:163], v[124:125], v[162:163]
	v_pk_add_f32 v[166:167], v[122:123], v[158:159]
	v_pk_add_f32 v[164:165], v[120:121], v[164:165]
	v_cvt_pk_bf16_f32 v122, v162, v163
	v_cvt_pk_bf16_f32 v123, v126, v127
	v_mul_f32_e32 v163, v163, v163
	v_cvt_pk_bf16_f32 v124, v164, v165
	v_cvt_pk_bf16_f32 v125, v166, v167
	v_mul_f32_e32 v127, v127, v127
	v_mul_f32_e32 v165, v165, v165
	v_mul_f32_e32 v167, v167, v167
	v_fmac_f32_e32 v163, v162, v162
	v_fmac_f32_e32 v127, v126, v126
	v_fmac_f32_e32 v165, v164, v164
	v_fmac_f32_e32 v167, v166, v166
	v_add_f32_e32 v126, v163, v127
	v_add_f32_e32 v127, v165, v167
	v_add_f32_e32 v164, v126, v127
	v_and_b32_e32 v121, 64, v154
	v_xor_b32_e32 v120, 16, v154
	v_add_u32_e32 v121, 64, v121
	v_cmp_lt_i32_e32 vcc, v120, v121
	global_store_dwordx4 v[160:161], v[122:125], off
	s_waitcnt vmcnt(13)
	v_mov_b32_e32 v156, v172
	v_mov_b32_e32 v157, v173
	v_mov_b32_e32 v158, v174
	v_mov_b32_e32 v159, v175
	v_lshlrev_b32_e32 v126, 16, v156
	v_and_b32_e32 v127, 0xffff0000, v156
	v_lshlrev_b32_e32 v156, 16, v157
	v_and_b32_e32 v157, 0xffff0000, v157
	v_lshlrev_b32_e32 v162, 16, v158
	v_and_b32_e32 v163, 0xffff0000, v158
	v_lshlrev_b32_e32 v158, 16, v159
	v_and_b32_e32 v159, 0xffff0000, v159
	v_pk_add_f32 v[118:119], v[118:119], v[156:157]
	v_pk_add_f32 v[116:117], v[116:117], v[126:127]
	v_pk_add_f32 v[126:127], v[114:115], v[158:159]
	v_pk_add_f32 v[156:157], v[112:113], v[162:163]
	v_mul_f32_e32 v112, v117, v117
	v_mul_f32_e32 v113, v119, v119
	v_mul_f32_e32 v114, v157, v157
	v_mul_f32_e32 v115, v127, v127
	v_fmac_f32_e32 v112, v116, v116
	v_fmac_f32_e32 v113, v118, v118
	v_fmac_f32_e32 v114, v156, v156
	v_fmac_f32_e32 v115, v126, v126
	v_add_f32_e32 v112, v112, v113
	v_add_f32_e32 v113, v114, v115
	v_cndmask_b32_e32 v120, v154, v120, vcc
	v_add_f32_e32 v112, v112, v113
	v_lshlrev_b32_e32 v120, 2, v120
	v_add_f32_e32 v112, v164, v112
	ds_bpermute_b32 v113, v120, v112
	v_cmp_lt_i32_e32 vcc, v155, v121
	v_cvt_pk_bf16_f32 v116, v116, v117
	v_cvt_pk_bf16_f32 v117, v118, v119
	v_cvt_pk_bf16_f32 v118, v156, v157
	s_waitcnt lgkmcnt(0)
	v_add_f32_e32 v112, v112, v113
	v_cvt_pk_bf16_f32 v119, v126, v127
	v_cndmask_b32_e32 v114, v154, v155, vcc
	v_lshlrev_b32_e32 v114, 2, v114
	ds_bpermute_b32 v113, v114, v112
	global_store_dwordx4 v[160:161], v[116:119], off offset:256
	s_and_saveexec_b64 s[58:59], s[2:3]
	s_cbranch_execz .LBB0_850
	s_waitcnt lgkmcnt(0)
	v_add_f32_e32 v115, v112, v113
	s_lshl_b32 s18, s64, 2
	v_lshlrev_b64 v[112:113], 7, v[146:147]
	s_ashr_i32 s19, s18, 31
	v_lshl_add_u64 v[112:113], s[48:49], 0, v[112:113]
	v_lshl_add_u64 v[112:113], s[18:19], 2, v[112:113]
	s_lshl_b32 s18, s70, 2
	s_mov_b32 s19, s23
	v_lshl_add_u64 v[112:113], v[112:113], 0, s[18:19]
	global_store_dword v[112:113], v115, off
; __device__ __forceinline__ unsigned cvt_pk_bf16(float lo, float hi) { unsigned r; asm volatile("v_cvt_pk_bf16_f32 %0, %1, %2" : "=v"(r) : "v"(lo), "v"(hi)); return r; }
; __device__ __forceinline__ float bf_lo(unsigned u) { return __uint_as_float(u << 16); }
; __device__ __forceinline__ float bf_hi(unsigned u) { return __uint_as_float(u & 0xffff0000u); }
;     __device__ __forceinline__ void operator()(const f32x4 (&acc)[2][2][4][2], const Unit& u, int wr, int wc, int fr, int fq) const {
;     ...
;         for (int ai = 0; ai < 2; ++ai)
; #pragma unroll
;             for (int m = 0; m < 4; ++m) { const int row = row0 + ai * HALF + m * 16; bf16_t* rowp = XB + (size_t)row * D + col0; float ss = 0.f;
; #pragma unroll
;                 for (int bj = 0; bj < 2; ++bj) { const u32x4 r = *(const u32x4*)(rowp + bj * HALF);
;                     const f32x4 o0 = (f32x4){bf_lo(r.x), bf_hi(r.x), bf_lo(r.y), bf_hi(r.y)} + acc[ai][bj][m][0] * alpha, o1 = (f32x4){bf_lo(r.z), bf_hi(r.z), bf_lo(r.w), bf_hi(r.w)} + acc[ai][bj][m][1] * alpha;
;                     ss += ((o0[0] * o0[0] + o0[1] * o0[1]) + (o0[2] * o0[2] + o0[3] * o0[3])) + ((o1[0] * o1[0] + o1[1] * o1[1]) + (o1[2] * o1[2] + o1[3] * o1[3]));
;                     u32x4 w; w.x = cvt_pk_bf16(o0[0], o0[1]); w.y = cvt_pk_bf16(o0[2], o0[3]); w.z = cvt_pk_bf16(o1[0], o1[1]); w.w = cvt_pk_bf16(o1[2], o1[3]);
;                     *(u32x4*)(rowp + bj * HALF) = w; }
;                 ss += __shfl_xor(ss, 16); ss += __shfl_xor(ss, 32);
;                 if (fq == 0) part[(size_t)row * NPART + u.pn * 4 + wc] = ss; }
.LBB0_850:
	s_or_b64 exec, exec, s[58:59]
	v_or_b32_e32 v112, 16, v146
	s_waitcnt lgkmcnt(0)
	v_ashrrev_i32_e32 v113, 31, v112
	v_lshlrev_b64 v[116:117], 12, v[112:113]
	v_lshl_add_u64 v[116:117], s[50:51], 0, v[116:117]
	v_lshl_add_u64 v[122:123], v[144:145], 1, v[116:117]
	s_waitcnt vmcnt(13)
	v_mov_b32_e32 v116, v176
	v_mov_b32_e32 v117, v177
	v_mov_b32_e32 v118, v178
	v_mov_b32_e32 v119, v179
	v_lshlrev_b32_e32 v124, 16, v116
	v_and_b32_e32 v125, 0xffff0000, v116
	v_lshlrev_b32_e32 v116, 16, v117
	v_and_b32_e32 v117, 0xffff0000, v117
	v_lshlrev_b32_e32 v126, 16, v118
	v_and_b32_e32 v127, 0xffff0000, v118
	v_lshlrev_b32_e32 v118, 16, v119
	v_and_b32_e32 v119, 0xffff0000, v119
	v_pk_add_f32 v[116:117], v[110:111], v[116:117]
	v_pk_add_f32 v[124:125], v[108:109], v[124:125]
	v_pk_add_f32 v[118:119], v[106:107], v[118:119]
	v_pk_add_f32 v[126:127], v[104:105], v[126:127]
	v_cvt_pk_bf16_f32 v104, v124, v125
	v_cvt_pk_bf16_f32 v105, v116, v117
	v_mul_f32_e32 v115, v125, v125
	v_cvt_pk_bf16_f32 v106, v126, v127
	v_cvt_pk_bf16_f32 v107, v118, v119
	v_mul_f32_e32 v117, v117, v117
	v_mul_f32_e32 v121, v127, v127
	v_mul_f32_e32 v119, v119, v119
	v_fmac_f32_e32 v115, v124, v124
	v_fmac_f32_e32 v117, v116, v116
	v_fmac_f32_e32 v121, v126, v126
	v_fmac_f32_e32 v119, v118, v118
	v_add_f32_e32 v115, v115, v117
	v_add_f32_e32 v116, v121, v119
	v_add_f32_e32 v115, v115, v116
	global_store_dwordx4 v[122:123], v[104:107], off
	s_waitcnt vmcnt(13)
	v_mov_b32_e32 v108, v180
	v_mov_b32_e32 v109, v181
	v_mov_b32_e32 v110, v182
	v_mov_b32_e32 v111, v183
	v_lshlrev_b32_e32 v116, 16, v108
	v_and_b32_e32 v117, 0xffff0000, v108
	v_lshlrev_b32_e32 v108, 16, v109
	v_and_b32_e32 v109, 0xffff0000, v109
	v_lshlrev_b32_e32 v118, 16, v110
	v_and_b32_e32 v119, 0xffff0000, v110
	v_lshlrev_b32_e32 v110, 16, v111
	v_and_b32_e32 v111, 0xffff0000, v111
	v_pk_add_f32 v[102:103], v[102:103], v[108:109]
	v_pk_add_f32 v[100:101], v[100:101], v[116:117]
	v_pk_add_f32 v[108:109], v[98:99], v[110:111]
	v_pk_add_f32 v[110:111], v[96:97], v[118:119]
	v_mul_f32_e32 v96, v101, v101
	v_mul_f32_e32 v97, v103, v103
	v_mul_f32_e32 v98, v111, v111
	v_mul_f32_e32 v99, v109, v109
	v_fmac_f32_e32 v96, v100, v100
	v_fmac_f32_e32 v97, v102, v102
	v_fmac_f32_e32 v98, v110, v110
	v_fmac_f32_e32 v99, v108, v108
	v_add_f32_e32 v96, v96, v97
	v_add_f32_e32 v97, v98, v99
	v_add_f32_e32 v96, v96, v97
	v_add_f32_e32 v96, v115, v96
	ds_bpermute_b32 v97, v120, v96
	v_cvt_pk_bf16_f32 v98, v100, v101
	v_cvt_pk_bf16_f32 v99, v102, v103
	v_cvt_pk_bf16_f32 v100, v110, v111
	v_cvt_pk_bf16_f32 v101, v108, v109
	s_waitcnt lgkmcnt(0)
	v_add_f32_e32 v96, v96, v97
	ds_bpermute_b32 v97, v114, v96
	global_store_dwordx4 v[122:123], v[98:101], off offset:256
	s_and_saveexec_b64 s[58:59], s[2:3]
	s_cbranch_execz .LBB0_852
	s_waitcnt lgkmcnt(0)
	v_add_f32_e32 v98, v96, v97
	s_lshl_b32 s18, s64, 2
	v_lshlrev_b64 v[96:97], 7, v[112:113]
	s_ashr_i32 s19, s18, 31
	v_lshl_add_u64 v[96:97], s[48:49], 0, v[96:97]
	v_lshl_add_u64 v[96:97], s[18:19], 2, v[96:97]
	s_lshl_b32 s18, s70, 2
	s_mov_b32 s19, s23
	v_lshl_add_u64 v[96:97], v[96:97], 0, s[18:19]
	global_store_dword v[96:97], v98, off
.LBB0_852:
	s_or_b64 exec, exec, s[58:59]
	v_or_b32_e32 v96, 32, v146
	s_waitcnt lgkmcnt(0)
	v_ashrrev_i32_e32 v97, 31, v96
	v_lshlrev_b64 v[98:99], 12, v[96:97]
	v_lshl_add_u64 v[98:99], s[50:51], 0, v[98:99]
	v_lshl_add_u64 v[102:103], v[144:145], 1, v[98:99]
	s_waitcnt vmcnt(13)
	v_mov_b32_e32 v98, v184
	v_mov_b32_e32 v99, v185
	v_mov_b32_e32 v100, v186
	v_mov_b32_e32 v101, v187
	v_lshlrev_b32_e32 v104, 16, v98
	v_and_b32_e32 v105, 0xffff0000, v98
	v_lshlrev_b32_e32 v98, 16, v99
	v_and_b32_e32 v99, 0xffff0000, v99
	v_lshlrev_b32_e32 v106, 16, v100
	v_and_b32_e32 v107, 0xffff0000, v100
	v_lshlrev_b32_e32 v100, 16, v101
	v_and_b32_e32 v101, 0xffff0000, v101
	v_pk_add_f32 v[98:99], v[94:95], v[98:99]
	v_pk_add_f32 v[104:105], v[92:93], v[104:105]
	v_pk_add_f32 v[100:101], v[90:91], v[100:101]
	v_pk_add_f32 v[106:107], v[88:89], v[106:107]
	v_cvt_pk_bf16_f32 v88, v104, v105
	v_cvt_pk_bf16_f32 v89, v98, v99
	v_mul_f32_e32 v105, v105, v105
	v_cvt_pk_bf16_f32 v90, v106, v107
	v_cvt_pk_bf16_f32 v91, v100, v101
	v_mul_f32_e32 v99, v99, v99
	v_mul_f32_e32 v107, v107, v107
	v_mul_f32_e32 v101, v101, v101
	v_fmac_f32_e32 v105, v104, v104
	v_fmac_f32_e32 v99, v98, v98
	v_fmac_f32_e32 v107, v106, v106
	v_fmac_f32_e32 v101, v100, v100
	v_add_f32_e32 v98, v105, v99
	v_add_f32_e32 v99, v107, v101
	v_add_f32_e32 v104, v98, v99
	global_store_dwordx4 v[102:103], v[88:91], off
	s_waitcnt vmcnt(13)
	v_mov_b32_e32 v92, v188
	v_mov_b32_e32 v93, v189
	v_mov_b32_e32 v94, v190
	v_mov_b32_e32 v95, v191
	v_lshlrev_b32_e32 v98, 16, v92
	v_and_b32_e32 v99, 0xffff0000, v92
	v_lshlrev_b32_e32 v92, 16, v93
	v_and_b32_e32 v93, 0xffff0000, v93
	v_lshlrev_b32_e32 v100, 16, v94
	v_and_b32_e32 v101, 0xffff0000, v94
	v_lshlrev_b32_e32 v94, 16, v95
	v_and_b32_e32 v95, 0xffff0000, v95
	v_pk_add_f32 v[86:87], v[86:87], v[92:93]
	v_pk_add_f32 v[84:85], v[84:85], v[98:99]
	v_pk_add_f32 v[92:93], v[82:83], v[94:95]
	v_pk_add_f32 v[94:95], v[80:81], v[100:101]
	v_mul_f32_e32 v80, v85, v85
	v_mul_f32_e32 v81, v87, v87
	v_mul_f32_e32 v82, v95, v95
	v_mul_f32_e32 v83, v93, v93
	v_fmac_f32_e32 v80, v84, v84
	v_fmac_f32_e32 v81, v86, v86
	v_fmac_f32_e32 v82, v94, v94
	v_fmac_f32_e32 v83, v92, v92
	v_add_f32_e32 v80, v80, v81
	v_add_f32_e32 v81, v82, v83
	v_add_f32_e32 v80, v80, v81
	v_add_f32_e32 v80, v104, v80
	ds_bpermute_b32 v81, v120, v80
	v_cvt_pk_bf16_f32 v82, v84, v85
	v_cvt_pk_bf16_f32 v83, v86, v87
	v_cvt_pk_bf16_f32 v84, v94, v95
	v_cvt_pk_bf16_f32 v85, v92, v93
	s_waitcnt lgkmcnt(0)
	v_add_f32_e32 v80, v80, v81
	ds_bpermute_b32 v81, v114, v80
	global_store_dwordx4 v[102:103], v[82:85], off offset:256
	s_and_saveexec_b64 s[58:59], s[2:3]
	s_cbranch_execz .LBB0_854
	s_waitcnt lgkmcnt(0)
	v_add_f32_e32 v82, v80, v81
	s_lshl_b32 s18, s64, 2
	v_lshlrev_b64 v[80:81], 7, v[96:97]
	s_ashr_i32 s19, s18, 31
	v_lshl_add_u64 v[80:81], s[48:49], 0, v[80:81]
	v_lshl_add_u64 v[80:81], s[18:19], 2, v[80:81]
	s_lshl_b32 s18, s70, 2
	s_mov_b32 s19, s23
	v_lshl_add_u64 v[80:81], v[80:81], 0, s[18:19]
	global_store_dword v[80:81], v82, off
; __device__ __forceinline__ unsigned cvt_pk_bf16(float lo, float hi) { unsigned r; asm volatile("v_cvt_pk_bf16_f32 %0, %1, %2" : "=v"(r) : "v"(lo), "v"(hi)); return r; }
; __device__ __forceinline__ float bf_lo(unsigned u) { return __uint_as_float(u << 16); }
; __device__ __forceinline__ float bf_hi(unsigned u) { return __uint_as_float(u & 0xffff0000u); }
;     __device__ __forceinline__ void operator()(const f32x4 (&acc)[2][2][4][2], const Unit& u, int wr, int wc, int fr, int fq) const {
;     ...
;         for (int ai = 0; ai < 2; ++ai)
; #pragma unroll
;             for (int m = 0; m < 4; ++m) { const int row = row0 + ai * HALF + m * 16; bf16_t* rowp = XB + (size_t)row * D + col0; float ss = 0.f;
; #pragma unroll
;                 for (int bj = 0; bj < 2; ++bj) { const u32x4 r = *(const u32x4*)(rowp + bj * HALF);
;                     const f32x4 o0 = (f32x4){bf_lo(r.x), bf_hi(r.x), bf_lo(r.y), bf_hi(r.y)} + acc[ai][bj][m][0] * alpha, o1 = (f32x4){bf_lo(r.z), bf_hi(r.z), bf_lo(r.w), bf_hi(r.w)} + acc[ai][bj][m][1] * alpha;
;                     ss += ((o0[0] * o0[0] + o0[1] * o0[1]) + (o0[2] * o0[2] + o0[3] * o0[3])) + ((o1[0] * o1[0] + o1[1] * o1[1]) + (o1[2] * o1[2] + o1[3] * o1[3]));
;                     u32x4 w; w.x = cvt_pk_bf16(o0[0], o0[1]); w.y = cvt_pk_bf16(o0[2], o0[3]); w.z = cvt_pk_bf16(o1[0], o1[1]); w.w = cvt_pk_bf16(o1[2], o1[3]);
;                     *(u32x4*)(rowp + bj * HALF) = w; }
;                 ss += __shfl_xor(ss, 16); ss += __shfl_xor(ss, 32);
;                 if (fq == 0) part[(size_t)row * NPART + u.pn * 4 + wc] = ss; }
.LBB0_854:
	s_or_b64 exec, exec, s[58:59]
	v_or_b32_e32 v80, 48, v146
	s_waitcnt lgkmcnt(0)
	v_ashrrev_i32_e32 v81, 31, v80
	v_lshlrev_b64 v[82:83], 12, v[80:81]
	v_lshl_add_u64 v[82:83], s[50:51], 0, v[82:83]
	v_lshl_add_u64 v[86:87], v[144:145], 1, v[82:83]
	s_waitcnt vmcnt(13)
	v_mov_b32_e32 v82, v192
	v_mov_b32_e32 v83, v193
	v_mov_b32_e32 v84, v194
	v_mov_b32_e32 v85, v195
	v_lshlrev_b32_e32 v88, 16, v82
	v_and_b32_e32 v89, 0xffff0000, v82
	v_lshlrev_b32_e32 v82, 16, v83
	v_and_b32_e32 v83, 0xffff0000, v83
	v_lshlrev_b32_e32 v90, 16, v84
	v_and_b32_e32 v91, 0xffff0000, v84
	v_lshlrev_b32_e32 v84, 16, v85
	v_and_b32_e32 v85, 0xffff0000, v85
	v_pk_add_f32 v[82:83], v[78:79], v[82:83]
	v_pk_add_f32 v[88:89], v[76:77], v[88:89]
	v_pk_add_f32 v[84:85], v[74:75], v[84:85]
	v_pk_add_f32 v[90:91], v[72:73], v[90:91]
	v_cvt_pk_bf16_f32 v72, v88, v89
	v_cvt_pk_bf16_f32 v73, v82, v83
	v_mul_f32_e32 v89, v89, v89
	v_cvt_pk_bf16_f32 v74, v90, v91
	v_cvt_pk_bf16_f32 v75, v84, v85
	v_mul_f32_e32 v83, v83, v83
	v_mul_f32_e32 v91, v91, v91
	v_mul_f32_e32 v85, v85, v85
	v_fmac_f32_e32 v89, v88, v88
	v_fmac_f32_e32 v83, v82, v82
	v_fmac_f32_e32 v91, v90, v90
	v_fmac_f32_e32 v85, v84, v84
	v_add_f32_e32 v82, v89, v83
	v_add_f32_e32 v83, v91, v85
	v_add_f32_e32 v88, v82, v83
	global_store_dwordx4 v[86:87], v[72:75], off
	s_waitcnt vmcnt(13)
	v_mov_b32_e32 v76, v196
	v_mov_b32_e32 v77, v197
	v_mov_b32_e32 v78, v198
	v_mov_b32_e32 v79, v199
	v_lshlrev_b32_e32 v82, 16, v76
	v_and_b32_e32 v83, 0xffff0000, v76
	v_lshlrev_b32_e32 v76, 16, v77
	v_and_b32_e32 v77, 0xffff0000, v77
	v_lshlrev_b32_e32 v84, 16, v78
	v_and_b32_e32 v85, 0xffff0000, v78
	v_lshlrev_b32_e32 v78, 16, v79
	v_and_b32_e32 v79, 0xffff0000, v79
	v_pk_add_f32 v[70:71], v[70:71], v[76:77]
	v_pk_add_f32 v[68:69], v[68:69], v[82:83]
	v_pk_add_f32 v[76:77], v[66:67], v[78:79]
	v_pk_add_f32 v[78:79], v[64:65], v[84:85]
	v_mul_f32_e32 v64, v69, v69
	v_mul_f32_e32 v65, v71, v71
	v_mul_f32_e32 v66, v79, v79
	v_mul_f32_e32 v67, v77, v77
	v_fmac_f32_e32 v64, v68, v68
	v_fmac_f32_e32 v65, v70, v70
	v_fmac_f32_e32 v66, v78, v78
	v_fmac_f32_e32 v67, v76, v76
	v_add_f32_e32 v64, v64, v65
	v_add_f32_e32 v65, v66, v67
	v_add_f32_e32 v64, v64, v65
	v_add_f32_e32 v64, v88, v64
	ds_bpermute_b32 v65, v120, v64
	v_cvt_pk_bf16_f32 v66, v68, v69
	v_cvt_pk_bf16_f32 v67, v70, v71
	v_cvt_pk_bf16_f32 v68, v78, v79
	v_cvt_pk_bf16_f32 v69, v76, v77
	s_waitcnt lgkmcnt(0)
	v_add_f32_e32 v64, v64, v65
	ds_bpermute_b32 v65, v114, v64
	global_store_dwordx4 v[86:87], v[66:69], off offset:256
	s_and_saveexec_b64 s[58:59], s[2:3]
	s_cbranch_execz .LBB0_856
	s_waitcnt lgkmcnt(0)
	v_add_f32_e32 v66, v64, v65
	s_lshl_b32 s18, s64, 2
	v_lshlrev_b64 v[64:65], 7, v[80:81]
	s_ashr_i32 s19, s18, 31
	v_lshl_add_u64 v[64:65], s[48:49], 0, v[64:65]
	v_lshl_add_u64 v[64:65], s[18:19], 2, v[64:65]
	s_lshl_b32 s18, s70, 2
	s_mov_b32 s19, s23
	v_lshl_add_u64 v[64:65], v[64:65], 0, s[18:19]
	global_store_dword v[64:65], v66, off
.LBB0_856:
	s_or_b64 exec, exec, s[58:59]
	v_add_u32_e32 v64, 0x80, v146
	s_waitcnt lgkmcnt(0)
	v_ashrrev_i32_e32 v65, 31, v64
	v_lshlrev_b64 v[66:67], 12, v[64:65]
	v_lshl_add_u64 v[66:67], s[50:51], 0, v[66:67]
	v_lshl_add_u64 v[70:71], v[144:145], 1, v[66:67]
	s_waitcnt vmcnt(13)
	v_mov_b32_e32 v66, v200
	v_mov_b32_e32 v67, v201
	v_mov_b32_e32 v68, v202
	v_mov_b32_e32 v69, v203
	v_lshlrev_b32_e32 v72, 16, v66
	v_and_b32_e32 v73, 0xffff0000, v66
	v_lshlrev_b32_e32 v66, 16, v67
	v_and_b32_e32 v67, 0xffff0000, v67
	v_lshlrev_b32_e32 v74, 16, v68
	v_and_b32_e32 v75, 0xffff0000, v68
	v_lshlrev_b32_e32 v68, 16, v69
	v_and_b32_e32 v69, 0xffff0000, v69
	v_pk_add_f32 v[66:67], v[62:63], v[66:67]
	v_pk_add_f32 v[72:73], v[60:61], v[72:73]
	v_pk_add_f32 v[68:69], v[58:59], v[68:69]
	v_pk_add_f32 v[74:75], v[56:57], v[74:75]
	v_cvt_pk_bf16_f32 v56, v72, v73
	v_cvt_pk_bf16_f32 v57, v66, v67
	v_mul_f32_e32 v73, v73, v73
	v_cvt_pk_bf16_f32 v58, v74, v75
	v_cvt_pk_bf16_f32 v59, v68, v69
	v_mul_f32_e32 v67, v67, v67
	v_mul_f32_e32 v75, v75, v75
	v_mul_f32_e32 v69, v69, v69
	v_fmac_f32_e32 v73, v72, v72
	v_fmac_f32_e32 v67, v66, v66
	v_fmac_f32_e32 v75, v74, v74
	v_fmac_f32_e32 v69, v68, v68
	v_add_f32_e32 v66, v73, v67
	v_add_f32_e32 v67, v75, v69
	v_add_f32_e32 v72, v66, v67
	global_store_dwordx4 v[70:71], v[56:59], off
	s_waitcnt vmcnt(13)
	v_mov_b32_e32 v60, v204
	v_mov_b32_e32 v61, v205
	v_mov_b32_e32 v62, v206
	v_mov_b32_e32 v63, v207
	v_lshlrev_b32_e32 v66, 16, v60
	v_and_b32_e32 v67, 0xffff0000, v60
	v_lshlrev_b32_e32 v60, 16, v61
	v_and_b32_e32 v61, 0xffff0000, v61
	v_lshlrev_b32_e32 v68, 16, v62
	v_and_b32_e32 v69, 0xffff0000, v62
	v_lshlrev_b32_e32 v62, 16, v63
	v_and_b32_e32 v63, 0xffff0000, v63
	v_pk_add_f32 v[54:55], v[54:55], v[60:61]
	v_pk_add_f32 v[52:53], v[52:53], v[66:67]
	v_pk_add_f32 v[60:61], v[50:51], v[62:63]
	v_pk_add_f32 v[62:63], v[48:49], v[68:69]
	v_mul_f32_e32 v48, v53, v53
	v_mul_f32_e32 v49, v55, v55
	v_mul_f32_e32 v50, v63, v63
	v_mul_f32_e32 v51, v61, v61
	v_fmac_f32_e32 v48, v52, v52
	v_fmac_f32_e32 v49, v54, v54
	v_fmac_f32_e32 v50, v62, v62
	v_fmac_f32_e32 v51, v60, v60
	v_add_f32_e32 v48, v48, v49
	v_add_f32_e32 v49, v50, v51
	v_add_f32_e32 v48, v48, v49
	v_add_f32_e32 v48, v72, v48
	ds_bpermute_b32 v49, v120, v48
	v_cvt_pk_bf16_f32 v50, v52, v53
	v_cvt_pk_bf16_f32 v51, v54, v55
	v_cvt_pk_bf16_f32 v52, v62, v63
	v_cvt_pk_bf16_f32 v53, v60, v61
	s_waitcnt lgkmcnt(0)
	v_add_f32_e32 v48, v48, v49
	ds_bpermute_b32 v49, v114, v48
	global_store_dwordx4 v[70:71], v[50:53], off offset:256
	s_and_saveexec_b64 s[58:59], s[2:3]
	s_cbranch_execz .LBB0_858
	s_waitcnt lgkmcnt(0)
	v_add_f32_e32 v50, v48, v49
	s_lshl_b32 s18, s64, 2
	v_lshlrev_b64 v[48:49], 7, v[64:65]
	s_ashr_i32 s19, s18, 31
	v_lshl_add_u64 v[48:49], s[48:49], 0, v[48:49]
	v_lshl_add_u64 v[48:49], s[18:19], 2, v[48:49]
	s_lshl_b32 s18, s70, 2
	s_mov_b32 s19, s23
	v_lshl_add_u64 v[48:49], v[48:49], 0, s[18:19]
	global_store_dword v[48:49], v50, off
; __device__ __forceinline__ unsigned cvt_pk_bf16(float lo, float hi) { unsigned r; asm volatile("v_cvt_pk_bf16_f32 %0, %1, %2" : "=v"(r) : "v"(lo), "v"(hi)); return r; }
; __device__ __forceinline__ float bf_lo(unsigned u) { return __uint_as_float(u << 16); }
; __device__ __forceinline__ float bf_hi(unsigned u) { return __uint_as_float(u & 0xffff0000u); }
;     __device__ __forceinline__ void operator()(const f32x4 (&acc)[2][2][4][2], const Unit& u, int wr, int wc, int fr, int fq) const {
;     ...
;         for (int ai = 0; ai < 2; ++ai)
; #pragma unroll
;             for (int m = 0; m < 4; ++m) { const int row = row0 + ai * HALF + m * 16; bf16_t* rowp = XB + (size_t)row * D + col0; float ss = 0.f;
; #pragma unroll
;                 for (int bj = 0; bj < 2; ++bj) { const u32x4 r = *(const u32x4*)(rowp + bj * HALF);
;                     const f32x4 o0 = (f32x4){bf_lo(r.x), bf_hi(r.x), bf_lo(r.y), bf_hi(r.y)} + acc[ai][bj][m][0] * alpha, o1 = (f32x4){bf_lo(r.z), bf_hi(r.z), bf_lo(r.w), bf_hi(r.w)} + acc[ai][bj][m][1] * alpha;
;                     ss += ((o0[0] * o0[0] + o0[1] * o0[1]) + (o0[2] * o0[2] + o0[3] * o0[3])) + ((o1[0] * o1[0] + o1[1] * o1[1]) + (o1[2] * o1[2] + o1[3] * o1[3]));
;                     u32x4 w; w.x = cvt_pk_bf16(o0[0], o0[1]); w.y = cvt_pk_bf16(o0[2], o0[3]); w.z = cvt_pk_bf16(o1[0], o1[1]); w.w = cvt_pk_bf16(o1[2], o1[3]);
;                     *(u32x4*)(rowp + bj * HALF) = w; }
;                 ss += __shfl_xor(ss, 16); ss += __shfl_xor(ss, 32);
;                 if (fq == 0) part[(size_t)row * NPART + u.pn * 4 + wc] = ss; }
.LBB0_858:
	s_or_b64 exec, exec, s[58:59]
	v_add_u32_e32 v48, 0x90, v146
	s_waitcnt lgkmcnt(0)
	v_ashrrev_i32_e32 v49, 31, v48
	v_lshlrev_b64 v[50:51], 12, v[48:49]
	v_lshl_add_u64 v[50:51], s[50:51], 0, v[50:51]
	v_lshl_add_u64 v[54:55], v[144:145], 1, v[50:51]
	s_waitcnt vmcnt(13)
	v_mov_b32_e32 v50, v208
	v_mov_b32_e32 v51, v209
	v_mov_b32_e32 v52, v210
	v_mov_b32_e32 v53, v211
	v_lshlrev_b32_e32 v56, 16, v50
	v_and_b32_e32 v57, 0xffff0000, v50
	v_lshlrev_b32_e32 v50, 16, v51
	v_and_b32_e32 v51, 0xffff0000, v51
	v_lshlrev_b32_e32 v58, 16, v52
	v_and_b32_e32 v59, 0xffff0000, v52
	v_lshlrev_b32_e32 v52, 16, v53
	v_and_b32_e32 v53, 0xffff0000, v53
	v_pk_add_f32 v[50:51], v[46:47], v[50:51]
	v_pk_add_f32 v[56:57], v[44:45], v[56:57]
	v_pk_add_f32 v[52:53], v[42:43], v[52:53]
	v_pk_add_f32 v[58:59], v[40:41], v[58:59]
	v_cvt_pk_bf16_f32 v40, v56, v57
	v_cvt_pk_bf16_f32 v41, v50, v51
	v_mul_f32_e32 v57, v57, v57
	v_cvt_pk_bf16_f32 v42, v58, v59
	v_cvt_pk_bf16_f32 v43, v52, v53
	v_mul_f32_e32 v51, v51, v51
	v_mul_f32_e32 v59, v59, v59
	v_mul_f32_e32 v53, v53, v53
	v_fmac_f32_e32 v57, v56, v56
	v_fmac_f32_e32 v51, v50, v50
	v_fmac_f32_e32 v59, v58, v58
	v_fmac_f32_e32 v53, v52, v52
	v_add_f32_e32 v50, v57, v51
	v_add_f32_e32 v51, v59, v53
	v_add_f32_e32 v56, v50, v51
	global_store_dwordx4 v[54:55], v[40:43], off
	s_waitcnt vmcnt(13)
	v_mov_b32_e32 v44, v212
	v_mov_b32_e32 v45, v213
	v_mov_b32_e32 v46, v214
	v_mov_b32_e32 v47, v215
	v_lshlrev_b32_e32 v50, 16, v44
	v_and_b32_e32 v51, 0xffff0000, v44
	v_lshlrev_b32_e32 v44, 16, v45
	v_and_b32_e32 v45, 0xffff0000, v45
	v_lshlrev_b32_e32 v52, 16, v46
	v_and_b32_e32 v53, 0xffff0000, v46
	v_lshlrev_b32_e32 v46, 16, v47
	v_and_b32_e32 v47, 0xffff0000, v47
	v_pk_add_f32 v[38:39], v[38:39], v[44:45]
	v_pk_add_f32 v[36:37], v[36:37], v[50:51]
	v_pk_add_f32 v[44:45], v[34:35], v[46:47]
	v_pk_add_f32 v[46:47], v[32:33], v[52:53]
	v_mul_f32_e32 v32, v37, v37
	v_mul_f32_e32 v33, v39, v39
	v_mul_f32_e32 v34, v47, v47
	v_mul_f32_e32 v35, v45, v45
	v_fmac_f32_e32 v32, v36, v36
	v_fmac_f32_e32 v33, v38, v38
	v_fmac_f32_e32 v34, v46, v46
	v_fmac_f32_e32 v35, v44, v44
	v_add_f32_e32 v32, v32, v33
	v_add_f32_e32 v33, v34, v35
	v_add_f32_e32 v32, v32, v33
	v_add_f32_e32 v32, v56, v32
	ds_bpermute_b32 v33, v120, v32
	v_cvt_pk_bf16_f32 v34, v36, v37
	v_cvt_pk_bf16_f32 v35, v38, v39
	v_cvt_pk_bf16_f32 v36, v46, v47
	v_cvt_pk_bf16_f32 v37, v44, v45
	s_waitcnt lgkmcnt(0)
	v_add_f32_e32 v32, v32, v33
	ds_bpermute_b32 v33, v114, v32
	global_store_dwordx4 v[54:55], v[34:37], off offset:256
	s_and_saveexec_b64 s[58:59], s[2:3]
	s_cbranch_execz .LBB0_860
	s_waitcnt lgkmcnt(0)
	v_add_f32_e32 v34, v32, v33
	s_lshl_b32 s18, s64, 2
	v_lshlrev_b64 v[32:33], 7, v[48:49]
	s_ashr_i32 s19, s18, 31
	v_lshl_add_u64 v[32:33], s[48:49], 0, v[32:33]
	v_lshl_add_u64 v[32:33], s[18:19], 2, v[32:33]
	s_lshl_b32 s18, s70, 2
	s_mov_b32 s19, s23
	v_lshl_add_u64 v[32:33], v[32:33], 0, s[18:19]
	global_store_dword v[32:33], v34, off
.LBB0_860:
	s_or_b64 exec, exec, s[58:59]
	v_add_u32_e32 v32, 0xa0, v146
	s_waitcnt lgkmcnt(0)
	v_ashrrev_i32_e32 v33, 31, v32
	v_lshlrev_b64 v[34:35], 12, v[32:33]
	v_lshl_add_u64 v[34:35], s[50:51], 0, v[34:35]
	v_lshl_add_u64 v[38:39], v[144:145], 1, v[34:35]
	s_waitcnt vmcnt(13)
	v_mov_b32_e32 v34, v216
	v_mov_b32_e32 v35, v217
	v_mov_b32_e32 v36, v218
	v_mov_b32_e32 v37, v219
	v_lshlrev_b32_e32 v40, 16, v34
	v_and_b32_e32 v41, 0xffff0000, v34
	v_lshlrev_b32_e32 v34, 16, v35
	v_and_b32_e32 v35, 0xffff0000, v35
	v_lshlrev_b32_e32 v42, 16, v36
	v_and_b32_e32 v43, 0xffff0000, v36
	v_lshlrev_b32_e32 v36, 16, v37
	v_and_b32_e32 v37, 0xffff0000, v37
	v_pk_add_f32 v[34:35], v[30:31], v[34:35]
	v_pk_add_f32 v[40:41], v[28:29], v[40:41]
	v_pk_add_f32 v[36:37], v[26:27], v[36:37]
	v_pk_add_f32 v[42:43], v[24:25], v[42:43]
	v_cvt_pk_bf16_f32 v24, v40, v41
	v_cvt_pk_bf16_f32 v25, v34, v35
	v_mul_f32_e32 v41, v41, v41
	v_cvt_pk_bf16_f32 v26, v42, v43
	v_cvt_pk_bf16_f32 v27, v36, v37
	v_mul_f32_e32 v35, v35, v35
	v_mul_f32_e32 v43, v43, v43
	v_mul_f32_e32 v37, v37, v37
	v_fmac_f32_e32 v41, v40, v40
	v_fmac_f32_e32 v35, v34, v34
	v_fmac_f32_e32 v43, v42, v42
	v_fmac_f32_e32 v37, v36, v36
	v_add_f32_e32 v34, v41, v35
	v_add_f32_e32 v35, v43, v37
	v_add_f32_e32 v40, v34, v35
	global_store_dwordx4 v[38:39], v[24:27], off
	s_waitcnt vmcnt(13)
	v_mov_b32_e32 v28, v222
	v_mov_b32_e32 v29, v223
	v_mov_b32_e32 v30, v224
	v_mov_b32_e32 v31, v225
	v_lshlrev_b32_e32 v34, 16, v28
	v_and_b32_e32 v35, 0xffff0000, v28
	v_lshlrev_b32_e32 v28, 16, v29
	v_and_b32_e32 v29, 0xffff0000, v29
	v_lshlrev_b32_e32 v36, 16, v30
	v_and_b32_e32 v37, 0xffff0000, v30
	v_lshlrev_b32_e32 v30, 16, v31
	v_and_b32_e32 v31, 0xffff0000, v31
	v_pk_add_f32 v[22:23], v[22:23], v[28:29]
	v_pk_add_f32 v[20:21], v[20:21], v[34:35]
	v_pk_add_f32 v[28:29], v[18:19], v[30:31]
	v_pk_add_f32 v[30:31], v[16:17], v[36:37]
	v_mul_f32_e32 v16, v21, v21
	v_mul_f32_e32 v17, v23, v23
	v_mul_f32_e32 v18, v31, v31
	v_mul_f32_e32 v19, v29, v29
	v_fmac_f32_e32 v16, v20, v20
	v_fmac_f32_e32 v17, v22, v22
	v_fmac_f32_e32 v18, v30, v30
	v_fmac_f32_e32 v19, v28, v28
	v_add_f32_e32 v16, v16, v17
	v_add_f32_e32 v17, v18, v19
	v_add_f32_e32 v16, v16, v17
	v_add_f32_e32 v16, v40, v16
	ds_bpermute_b32 v17, v120, v16
	v_cvt_pk_bf16_f32 v18, v20, v21
	v_cvt_pk_bf16_f32 v19, v22, v23
	v_cvt_pk_bf16_f32 v20, v30, v31
	v_cvt_pk_bf16_f32 v21, v28, v29
	s_waitcnt lgkmcnt(0)
	v_add_f32_e32 v16, v16, v17
	ds_bpermute_b32 v17, v114, v16
	global_store_dwordx4 v[38:39], v[18:21], off offset:256
	s_and_saveexec_b64 s[58:59], s[2:3]
	s_cbranch_execz .LBB0_862
	s_waitcnt lgkmcnt(0)
	v_add_f32_e32 v18, v16, v17
	s_lshl_b32 s18, s64, 2
	v_lshlrev_b64 v[16:17], 7, v[32:33]
	s_ashr_i32 s19, s18, 31
	v_lshl_add_u64 v[16:17], s[48:49], 0, v[16:17]
	v_lshl_add_u64 v[16:17], s[18:19], 2, v[16:17]
	s_lshl_b32 s18, s70, 2
	s_mov_b32 s19, s23
	v_lshl_add_u64 v[16:17], v[16:17], 0, s[18:19]
	global_store_dword v[16:17], v18, off

; __device__ __forceinline__ unsigned cvt_pk_bf16(float lo, float hi) { unsigned r; asm volatile("v_cvt_pk_bf16_f32 %0, %1, %2" : "=v"(r) : "v"(lo), "v"(hi)); return r; }
; __device__ __forceinline__ float bf_lo(unsigned u) { return __uint_as_float(u << 16); }
; __device__ __forceinline__ float bf_hi(unsigned u) { return __uint_as_float(u & 0xffff0000u); }
;     __device__ __forceinline__ void operator()(const f32x4 (&acc)[2][2][4][2], const Unit& u, int wr, int wc, int fr, int fq) const {
;         const int row0 = u.pm * BM + wr * 64 + fr, col0 = u.pn * BM + wc * 32 + 8 * fq;
; #pragma unroll
;         for (int ai = 0; ai < 2; ++ai)
; #pragma unroll
;             for (int m = 0; m < 4; ++m) { const int row = row0 + ai * HALF + m * 16; bf16_t* rowp = XB + (size_t)row * D + col0; float ss = 0.f;
; #pragma unroll
;                 for (int bj = 0; bj < 2; ++bj) { const u32x4 r = *(const u32x4*)(rowp + bj * HALF);
;                     const f32x4 o0 = (f32x4){bf_lo(r.x), bf_hi(r.x), bf_lo(r.y), bf_hi(r.y)} + acc[ai][bj][m][0] * alpha, o1 = (f32x4){bf_lo(r.z), bf_hi(r.z), bf_lo(r.w), bf_hi(r.w)} + acc[ai][bj][m][1] * alpha;
;                     ss += ((o0[0] * o0[0] + o0[1] * o0[1]) + (o0[2] * o0[2] + o0[3] * o0[3])) + ((o1[0] * o1[0] + o1[1] * o1[1]) + (o1[2] * o1[2] + o1[3] * o1[3]));
;                     u32x4 w; w.x = cvt_pk_bf16(o0[0], o0[1]); w.y = cvt_pk_bf16(o0[2], o0[3]); w.z = cvt_pk_bf16(o1[0], o1[1]); w.w = cvt_pk_bf16(o1[2], o1[3]);
;                     *(u32x4*)(rowp + bj * HALF) = w; }
;                 ss += __shfl_xor(ss, 16); ss += __shfl_xor(ss, 32);
;                 if (fq == 0) part[(size_t)row * NPART + u.pn * 4 + wc] = ss; }
.LBB0_1068:
	v_lshl_add_u32 v146, s79, 8, v148
	v_ashrrev_i32_e32 v147, 31, v146
	v_lshl_or_b32 v144, s58, 8, v150
	v_lshlrev_b64 v[156:157], 12, v[146:147]
	v_ashrrev_i32_e32 v145, 31, v144
	v_mov_b32_e32 v226, v146
	v_ashrrev_i32_e32 v227, 31, v226
	v_lshlrev_b64 v[226:227], 12, v[226:227]
	v_lshl_add_u64 v[226:227], s[50:51], 0, v[226:227]
	v_lshl_add_u64 v[226:227], v[144:145], 1, v[226:227]
	global_load_dwordx4 v[168:171], v[226:227], off
	global_load_dwordx4 v[172:175], v[226:227], off offset:256
	v_add_u32_e32 v226, 0x10, v146
	v_ashrrev_i32_e32 v227, 31, v226
	v_lshlrev_b64 v[226:227], 12, v[226:227]
	v_lshl_add_u64 v[226:227], s[50:51], 0, v[226:227]
	v_lshl_add_u64 v[226:227], v[144:145], 1, v[226:227]
	global_load_dwordx4 v[176:179], v[226:227], off
	global_load_dwordx4 v[180:183], v[226:227], off offset:256
	v_add_u32_e32 v226, 0x20, v146
	v_ashrrev_i32_e32 v227, 31, v226
	v_lshlrev_b64 v[226:227], 12, v[226:227]
	v_lshl_add_u64 v[226:227], s[50:51], 0, v[226:227]
	v_lshl_add_u64 v[226:227], v[144:145], 1, v[226:227]
	global_load_dwordx4 v[184:187], v[226:227], off
	global_load_dwordx4 v[188:191], v[226:227], off offset:256
	v_add_u32_e32 v226, 0x30, v146
	v_ashrrev_i32_e32 v227, 31, v226
	v_lshlrev_b64 v[226:227], 12, v[226:227]
	v_lshl_add_u64 v[226:227], s[50:51], 0, v[226:227]
	v_lshl_add_u64 v[226:227], v[144:145], 1, v[226:227]
	global_load_dwordx4 v[192:195], v[226:227], off
	global_load_dwordx4 v[196:199], v[226:227], off offset:256
	v_add_u32_e32 v226, 0x80, v146
	v_ashrrev_i32_e32 v227, 31, v226
	v_lshlrev_b64 v[226:227], 12, v[226:227]
	v_lshl_add_u64 v[226:227], s[50:51], 0, v[226:227]
	v_lshl_add_u64 v[226:227], v[144:145], 1, v[226:227]
	global_load_dwordx4 v[200:203], v[226:227], off
	global_load_dwordx4 v[204:207], v[226:227], off offset:256
	v_add_u32_e32 v226, 0x90, v146
	v_ashrrev_i32_e32 v227, 31, v226
	v_lshlrev_b64 v[226:227], 12, v[226:227]
	v_lshl_add_u64 v[226:227], s[50:51], 0, v[226:227]
	v_lshl_add_u64 v[226:227], v[144:145], 1, v[226:227]
	global_load_dwordx4 v[208:211], v[226:227], off
	global_load_dwordx4 v[212:215], v[226:227], off offset:256
	v_add_u32_e32 v226, 0xa0, v146
	v_ashrrev_i32_e32 v227, 31, v226
	v_lshlrev_b64 v[226:227], 12, v[226:227]
	v_lshl_add_u64 v[226:227], s[50:51], 0, v[226:227]
	v_lshl_add_u64 v[226:227], v[144:145], 1, v[226:227]
	global_load_dwordx4 v[216:219], v[226:227], off
	global_load_dwordx4 v[222:225], v[226:227], off offset:256
	v_lshl_add_u64 v[156:157], s[50:51], 0, v[156:157]
	v_lshl_add_u64 v[160:161], v[144:145], 1, v[156:157]
	v_xor_b32_e32 v155, 32, v154
	s_waitcnt vmcnt(13)
	v_mov_b32_e32 v156, v168
	v_mov_b32_e32 v157, v169
	v_mov_b32_e32 v158, v170
	v_mov_b32_e32 v159, v171
	v_lshlrev_b32_e32 v162, 16, v156
	v_and_b32_e32 v163, 0xffff0000, v156
	v_lshlrev_b32_e32 v156, 16, v157
	v_and_b32_e32 v157, 0xffff0000, v157
	v_lshlrev_b32_e32 v164, 16, v158
	v_and_b32_e32 v165, 0xffff0000, v158
	v_lshlrev_b32_e32 v158, 16, v159
	v_and_b32_e32 v159, 0xffff0000, v159
	v_pk_add_f32 v[126:127], v[126:127], v[156:157]
	v_pk_add_f32 v[162:163], v[124:125], v[162:163]
	v_pk_add_f32 v[166:167], v[122:123], v[158:159]
	v_pk_add_f32 v[164:165], v[120:121], v[164:165]
	v_cvt_pk_bf16_f32 v122, v162, v163
	v_cvt_pk_bf16_f32 v123, v126, v127
	v_mul_f32_e32 v163, v163, v163
	v_cvt_pk_bf16_f32 v124, v164, v165
	v_cvt_pk_bf16_f32 v125, v166, v167
	v_mul_f32_e32 v127, v127, v127
	v_mul_f32_e32 v165, v165, v165
	v_mul_f32_e32 v167, v167, v167
	v_fmac_f32_e32 v163, v162, v162
	v_fmac_f32_e32 v127, v126, v126
	v_fmac_f32_e32 v165, v164, v164
	v_fmac_f32_e32 v167, v166, v166
	v_add_f32_e32 v126, v163, v127
	v_add_f32_e32 v127, v165, v167
	v_add_f32_e32 v164, v126, v127
	v_and_b32_e32 v121, 64, v154
	v_xor_b32_e32 v120, 16, v154
	v_add_u32_e32 v121, 64, v121
	v_cmp_lt_i32_e32 vcc, v120, v121
	global_store_dwordx4 v[160:161], v[122:125], off
	s_waitcnt vmcnt(13)
	v_mov_b32_e32 v156, v172
	v_mov_b32_e32 v157, v173
	v_mov_b32_e32 v158, v174
	v_mov_b32_e32 v159, v175
	v_lshlrev_b32_e32 v126, 16, v156
	v_and_b32_e32 v127, 0xffff0000, v156
	v_lshlrev_b32_e32 v156, 16, v157
	v_and_b32_e32 v157, 0xffff0000, v157
	v_lshlrev_b32_e32 v162, 16, v158
	v_and_b32_e32 v163, 0xffff0000, v158
	v_lshlrev_b32_e32 v158, 16, v159
	v_and_b32_e32 v159, 0xffff0000, v159
	v_pk_add_f32 v[118:119], v[118:119], v[156:157]
	v_pk_add_f32 v[116:117], v[116:117], v[126:127]
	v_pk_add_f32 v[126:127], v[114:115], v[158:159]
	v_pk_add_f32 v[156:157], v[112:113], v[162:163]
	v_mul_f32_e32 v112, v117, v117
	v_mul_f32_e32 v113, v119, v119
	v_mul_f32_e32 v114, v157, v157
	v_mul_f32_e32 v115, v127, v127
	v_fmac_f32_e32 v112, v116, v116
	v_fmac_f32_e32 v113, v118, v118
	v_fmac_f32_e32 v114, v156, v156
	v_fmac_f32_e32 v115, v126, v126
	v_add_f32_e32 v112, v112, v113
	v_add_f32_e32 v113, v114, v115
	v_cndmask_b32_e32 v120, v154, v120, vcc
	v_add_f32_e32 v112, v112, v113
	v_lshlrev_b32_e32 v120, 2, v120
	v_add_f32_e32 v112, v164, v112
	ds_bpermute_b32 v113, v120, v112
	v_cmp_lt_i32_e32 vcc, v155, v121
	v_cvt_pk_bf16_f32 v116, v116, v117
	v_cvt_pk_bf16_f32 v117, v118, v119
	v_cvt_pk_bf16_f32 v118, v156, v157
	s_waitcnt lgkmcnt(0)
	v_add_f32_e32 v112, v112, v113
	v_cvt_pk_bf16_f32 v119, v126, v127
	v_cndmask_b32_e32 v114, v154, v155, vcc
	v_lshlrev_b32_e32 v114, 2, v114
	ds_bpermute_b32 v113, v114, v112
	global_store_dwordx4 v[160:161], v[116:119], off offset:256
	s_and_saveexec_b64 s[52:53], s[2:3]
	s_cbranch_execz .LBB0_1070
	s_waitcnt lgkmcnt(0)
	v_add_f32_e32 v115, v112, v113
	s_lshl_b32 s18, s58, 2
	v_lshlrev_b64 v[112:113], 7, v[146:147]
	s_ashr_i32 s19, s18, 31
	v_lshl_add_u64 v[112:113], s[48:49], 0, v[112:113]
	v_lshl_add_u64 v[112:113], s[18:19], 2, v[112:113]
	s_lshl_b32 s18, s64, 2
	s_mov_b32 s19, s21
	v_lshl_add_u64 v[112:113], v[112:113], 0, s[18:19]
	global_store_dword v[112:113], v115, off
; __device__ __forceinline__ unsigned cvt_pk_bf16(float lo, float hi) { unsigned r; asm volatile("v_cvt_pk_bf16_f32 %0, %1, %2" : "=v"(r) : "v"(lo), "v"(hi)); return r; }
; __device__ __forceinline__ float bf_lo(unsigned u) { return __uint_as_float(u << 16); }
; __device__ __forceinline__ float bf_hi(unsigned u) { return __uint_as_float(u & 0xffff0000u); }
;     __device__ __forceinline__ void operator()(const f32x4 (&acc)[2][2][4][2], const Unit& u, int wr, int wc, int fr, int fq) const {
;     ...
;         for (int ai = 0; ai < 2; ++ai)
; #pragma unroll
;             for (int m = 0; m < 4; ++m) { const int row = row0 + ai * HALF + m * 16; bf16_t* rowp = XB + (size_t)row * D + col0; float ss = 0.f;
; #pragma unroll
;                 for (int bj = 0; bj < 2; ++bj) { const u32x4 r = *(const u32x4*)(rowp + bj * HALF);
;                     const f32x4 o0 = (f32x4){bf_lo(r.x), bf_hi(r.x), bf_lo(r.y), bf_hi(r.y)} + acc[ai][bj][m][0] * alpha, o1 = (f32x4){bf_lo(r.z), bf_hi(r.z), bf_lo(r.w), bf_hi(r.w)} + acc[ai][bj][m][1] * alpha;
;                     ss += ((o0[0] * o0[0] + o0[1] * o0[1]) + (o0[2] * o0[2] + o0[3] * o0[3])) + ((o1[0] * o1[0] + o1[1] * o1[1]) + (o1[2] * o1[2] + o1[3] * o1[3]));
;                     u32x4 w; w.x = cvt_pk_bf16(o0[0], o0[1]); w.y = cvt_pk_bf16(o0[2], o0[3]); w.z = cvt_pk_bf16(o1[0], o1[1]); w.w = cvt_pk_bf16(o1[2], o1[3]);
;                     *(u32x4*)(rowp + bj * HALF) = w; }
;                 ss += __shfl_xor(ss, 16); ss += __shfl_xor(ss, 32);
;                 if (fq == 0) part[(size_t)row * NPART + u.pn * 4 + wc] = ss; }
.LBB0_1070:
	s_or_b64 exec, exec, s[52:53]
	v_or_b32_e32 v112, 16, v146
	s_waitcnt lgkmcnt(0)
	v_ashrrev_i32_e32 v113, 31, v112
	v_lshlrev_b64 v[116:117], 12, v[112:113]
	v_lshl_add_u64 v[116:117], s[50:51], 0, v[116:117]
	v_lshl_add_u64 v[122:123], v[144:145], 1, v[116:117]
	s_waitcnt vmcnt(13)
	v_mov_b32_e32 v116, v176
	v_mov_b32_e32 v117, v177
	v_mov_b32_e32 v118, v178
	v_mov_b32_e32 v119, v179
	v_lshlrev_b32_e32 v124, 16, v116
	v_and_b32_e32 v125, 0xffff0000, v116
	v_lshlrev_b32_e32 v116, 16, v117
	v_and_b32_e32 v117, 0xffff0000, v117
	v_lshlrev_b32_e32 v126, 16, v118
	v_and_b32_e32 v127, 0xffff0000, v118
	v_lshlrev_b32_e32 v118, 16, v119
	v_and_b32_e32 v119, 0xffff0000, v119
	v_pk_add_f32 v[116:117], v[110:111], v[116:117]
	v_pk_add_f32 v[124:125], v[108:109], v[124:125]
	v_pk_add_f32 v[118:119], v[106:107], v[118:119]
	v_pk_add_f32 v[126:127], v[104:105], v[126:127]
	v_cvt_pk_bf16_f32 v104, v124, v125
	v_cvt_pk_bf16_f32 v105, v116, v117
	v_mul_f32_e32 v115, v125, v125
	v_cvt_pk_bf16_f32 v106, v126, v127
	v_cvt_pk_bf16_f32 v107, v118, v119
	v_mul_f32_e32 v117, v117, v117
	v_mul_f32_e32 v121, v127, v127
	v_mul_f32_e32 v119, v119, v119
	v_fmac_f32_e32 v115, v124, v124
	v_fmac_f32_e32 v117, v116, v116
	v_fmac_f32_e32 v121, v126, v126
	v_fmac_f32_e32 v119, v118, v118
	v_add_f32_e32 v115, v115, v117
	v_add_f32_e32 v116, v121, v119
	v_add_f32_e32 v115, v115, v116
	global_store_dwordx4 v[122:123], v[104:107], off
	s_waitcnt vmcnt(13)
	v_mov_b32_e32 v108, v180
	v_mov_b32_e32 v109, v181
	v_mov_b32_e32 v110, v182
	v_mov_b32_e32 v111, v183
	v_lshlrev_b32_e32 v116, 16, v108
	v_and_b32_e32 v117, 0xffff0000, v108
	v_lshlrev_b32_e32 v108, 16, v109
	v_and_b32_e32 v109, 0xffff0000, v109
	v_lshlrev_b32_e32 v118, 16, v110
	v_and_b32_e32 v119, 0xffff0000, v110
	v_lshlrev_b32_e32 v110, 16, v111
	v_and_b32_e32 v111, 0xffff0000, v111
	v_pk_add_f32 v[102:103], v[102:103], v[108:109]
	v_pk_add_f32 v[100:101], v[100:101], v[116:117]
	v_pk_add_f32 v[108:109], v[98:99], v[110:111]
	v_pk_add_f32 v[110:111], v[96:97], v[118:119]
	v_mul_f32_e32 v96, v101, v101
	v_mul_f32_e32 v97, v103, v103
	v_mul_f32_e32 v98, v111, v111
	v_mul_f32_e32 v99, v109, v109
	v_fmac_f32_e32 v96, v100, v100
	v_fmac_f32_e32 v97, v102, v102
	v_fmac_f32_e32 v98, v110, v110
	v_fmac_f32_e32 v99, v108, v108
	v_add_f32_e32 v96, v96, v97
	v_add_f32_e32 v97, v98, v99
	v_add_f32_e32 v96, v96, v97
	v_add_f32_e32 v96, v115, v96
	ds_bpermute_b32 v97, v120, v96
	v_cvt_pk_bf16_f32 v98, v100, v101
	v_cvt_pk_bf16_f32 v99, v102, v103
	v_cvt_pk_bf16_f32 v100, v110, v111
	v_cvt_pk_bf16_f32 v101, v108, v109
	s_waitcnt lgkmcnt(0)
	v_add_f32_e32 v96, v96, v97
	ds_bpermute_b32 v97, v114, v96
	global_store_dwordx4 v[122:123], v[98:101], off offset:256
	s_and_saveexec_b64 s[52:53], s[2:3]
	s_cbranch_execz .LBB0_1072
	s_waitcnt lgkmcnt(0)
	v_add_f32_e32 v98, v96, v97
	s_lshl_b32 s18, s58, 2
	v_lshlrev_b64 v[96:97], 7, v[112:113]
	s_ashr_i32 s19, s18, 31
	v_lshl_add_u64 v[96:97], s[48:49], 0, v[96:97]
	v_lshl_add_u64 v[96:97], s[18:19], 2, v[96:97]
	s_lshl_b32 s18, s64, 2
	s_mov_b32 s19, s21
	v_lshl_add_u64 v[96:97], v[96:97], 0, s[18:19]
	global_store_dword v[96:97], v98, off
.LBB0_1072:
	s_or_b64 exec, exec, s[52:53]
	v_or_b32_e32 v96, 32, v146
	s_waitcnt lgkmcnt(0)
	v_ashrrev_i32_e32 v97, 31, v96
	v_lshlrev_b64 v[98:99], 12, v[96:97]
	v_lshl_add_u64 v[98:99], s[50:51], 0, v[98:99]
	v_lshl_add_u64 v[102:103], v[144:145], 1, v[98:99]
	s_waitcnt vmcnt(13)
	v_mov_b32_e32 v98, v184
	v_mov_b32_e32 v99, v185
	v_mov_b32_e32 v100, v186
	v_mov_b32_e32 v101, v187
	v_lshlrev_b32_e32 v104, 16, v98
	v_and_b32_e32 v105, 0xffff0000, v98
	v_lshlrev_b32_e32 v98, 16, v99
	v_and_b32_e32 v99, 0xffff0000, v99
	v_lshlrev_b32_e32 v106, 16, v100
	v_and_b32_e32 v107, 0xffff0000, v100
	v_lshlrev_b32_e32 v100, 16, v101
	v_and_b32_e32 v101, 0xffff0000, v101
	v_pk_add_f32 v[98:99], v[94:95], v[98:99]
	v_pk_add_f32 v[104:105], v[92:93], v[104:105]
	v_pk_add_f32 v[100:101], v[90:91], v[100:101]
	v_pk_add_f32 v[106:107], v[88:89], v[106:107]
	v_cvt_pk_bf16_f32 v88, v104, v105
	v_cvt_pk_bf16_f32 v89, v98, v99
	v_mul_f32_e32 v105, v105, v105
	v_cvt_pk_bf16_f32 v90, v106, v107
	v_cvt_pk_bf16_f32 v91, v100, v101
	v_mul_f32_e32 v99, v99, v99
	v_mul_f32_e32 v107, v107, v107
	v_mul_f32_e32 v101, v101, v101
	v_fmac_f32_e32 v105, v104, v104
	v_fmac_f32_e32 v99, v98, v98
	v_fmac_f32_e32 v107, v106, v106
	v_fmac_f32_e32 v101, v100, v100
	v_add_f32_e32 v98, v105, v99
	v_add_f32_e32 v99, v107, v101
	v_add_f32_e32 v104, v98, v99
	global_store_dwordx4 v[102:103], v[88:91], off
	s_waitcnt vmcnt(13)
	v_mov_b32_e32 v92, v188
	v_mov_b32_e32 v93, v189
	v_mov_b32_e32 v94, v190
	v_mov_b32_e32 v95, v191
	v_lshlrev_b32_e32 v98, 16, v92
	v_and_b32_e32 v99, 0xffff0000, v92
	v_lshlrev_b32_e32 v92, 16, v93
	v_and_b32_e32 v93, 0xffff0000, v93
	v_lshlrev_b32_e32 v100, 16, v94
	v_and_b32_e32 v101, 0xffff0000, v94
	v_lshlrev_b32_e32 v94, 16, v95
	v_and_b32_e32 v95, 0xffff0000, v95
	v_pk_add_f32 v[86:87], v[86:87], v[92:93]
	v_pk_add_f32 v[84:85], v[84:85], v[98:99]
	v_pk_add_f32 v[92:93], v[82:83], v[94:95]
	v_pk_add_f32 v[94:95], v[80:81], v[100:101]
	v_mul_f32_e32 v80, v85, v85
	v_mul_f32_e32 v81, v87, v87
	v_mul_f32_e32 v82, v95, v95
	v_mul_f32_e32 v83, v93, v93
	v_fmac_f32_e32 v80, v84, v84
	v_fmac_f32_e32 v81, v86, v86
	v_fmac_f32_e32 v82, v94, v94
	v_fmac_f32_e32 v83, v92, v92
	v_add_f32_e32 v80, v80, v81
	v_add_f32_e32 v81, v82, v83
	v_add_f32_e32 v80, v80, v81
	v_add_f32_e32 v80, v104, v80
	ds_bpermute_b32 v81, v120, v80
	v_cvt_pk_bf16_f32 v82, v84, v85
	v_cvt_pk_bf16_f32 v83, v86, v87
	v_cvt_pk_bf16_f32 v84, v94, v95
	v_cvt_pk_bf16_f32 v85, v92, v93
	s_waitcnt lgkmcnt(0)
	v_add_f32_e32 v80, v80, v81
	ds_bpermute_b32 v81, v114, v80
	global_store_dwordx4 v[102:103], v[82:85], off offset:256
	s_and_saveexec_b64 s[52:53], s[2:3]
	s_cbranch_execz .LBB0_1074
	s_waitcnt lgkmcnt(0)
	v_add_f32_e32 v82, v80, v81
	s_lshl_b32 s18, s58, 2
	v_lshlrev_b64 v[80:81], 7, v[96:97]
	s_ashr_i32 s19, s18, 31
	v_lshl_add_u64 v[80:81], s[48:49], 0, v[80:81]
	v_lshl_add_u64 v[80:81], s[18:19], 2, v[80:81]
	s_lshl_b32 s18, s64, 2
	s_mov_b32 s19, s21
	v_lshl_add_u64 v[80:81], v[80:81], 0, s[18:19]
	global_store_dword v[80:81], v82, off
; __device__ __forceinline__ unsigned cvt_pk_bf16(float lo, float hi) { unsigned r; asm volatile("v_cvt_pk_bf16_f32 %0, %1, %2" : "=v"(r) : "v"(lo), "v"(hi)); return r; }
; __device__ __forceinline__ float bf_lo(unsigned u) { return __uint_as_float(u << 16); }
; __device__ __forceinline__ float bf_hi(unsigned u) { return __uint_as_float(u & 0xffff0000u); }
;     __device__ __forceinline__ void operator()(const f32x4 (&acc)[2][2][4][2], const Unit& u, int wr, int wc, int fr, int fq) const {
;     ...
;         for (int ai = 0; ai < 2; ++ai)
; #pragma unroll
;             for (int m = 0; m < 4; ++m) { const int row = row0 + ai * HALF + m * 16; bf16_t* rowp = XB + (size_t)row * D + col0; float ss = 0.f;
; #pragma unroll
;                 for (int bj = 0; bj < 2; ++bj) { const u32x4 r = *(const u32x4*)(rowp + bj * HALF);
;                     const f32x4 o0 = (f32x4){bf_lo(r.x), bf_hi(r.x), bf_lo(r.y), bf_hi(r.y)} + acc[ai][bj][m][0] * alpha, o1 = (f32x4){bf_lo(r.z), bf_hi(r.z), bf_lo(r.w), bf_hi(r.w)} + acc[ai][bj][m][1] * alpha;
;                     ss += ((o0[0] * o0[0] + o0[1] * o0[1]) + (o0[2] * o0[2] + o0[3] * o0[3])) + ((o1[0] * o1[0] + o1[1] * o1[1]) + (o1[2] * o1[2] + o1[3] * o1[3]));
;                     u32x4 w; w.x = cvt_pk_bf16(o0[0], o0[1]); w.y = cvt_pk_bf16(o0[2], o0[3]); w.z = cvt_pk_bf16(o1[0], o1[1]); w.w = cvt_pk_bf16(o1[2], o1[3]);
;                     *(u32x4*)(rowp + bj * HALF) = w; }
;                 ss += __shfl_xor(ss, 16); ss += __shfl_xor(ss, 32);
;                 if (fq == 0) part[(size_t)row * NPART + u.pn * 4 + wc] = ss; }
.LBB0_1074:
	s_or_b64 exec, exec, s[52:53]
	v_or_b32_e32 v80, 48, v146
	s_waitcnt lgkmcnt(0)
	v_ashrrev_i32_e32 v81, 31, v80
	v_lshlrev_b64 v[82:83], 12, v[80:81]
	v_lshl_add_u64 v[82:83], s[50:51], 0, v[82:83]
	v_lshl_add_u64 v[86:87], v[144:145], 1, v[82:83]
	s_waitcnt vmcnt(13)
	v_mov_b32_e32 v82, v192
	v_mov_b32_e32 v83, v193
	v_mov_b32_e32 v84, v194
	v_mov_b32_e32 v85, v195
	v_lshlrev_b32_e32 v88, 16, v82
	v_and_b32_e32 v89, 0xffff0000, v82
	v_lshlrev_b32_e32 v82, 16, v83
	v_and_b32_e32 v83, 0xffff0000, v83
	v_lshlrev_b32_e32 v90, 16, v84
	v_and_b32_e32 v91, 0xffff0000, v84
	v_lshlrev_b32_e32 v84, 16, v85
	v_and_b32_e32 v85, 0xffff0000, v85
	v_pk_add_f32 v[82:83], v[78:79], v[82:83]
	v_pk_add_f32 v[88:89], v[76:77], v[88:89]
	v_pk_add_f32 v[84:85], v[74:75], v[84:85]
	v_pk_add_f32 v[90:91], v[72:73], v[90:91]
	v_cvt_pk_bf16_f32 v72, v88, v89
	v_cvt_pk_bf16_f32 v73, v82, v83
	v_mul_f32_e32 v89, v89, v89
	v_cvt_pk_bf16_f32 v74, v90, v91
	v_cvt_pk_bf16_f32 v75, v84, v85
	v_mul_f32_e32 v83, v83, v83
	v_mul_f32_e32 v91, v91, v91
	v_mul_f32_e32 v85, v85, v85
	v_fmac_f32_e32 v89, v88, v88
	v_fmac_f32_e32 v83, v82, v82
	v_fmac_f32_e32 v91, v90, v90
	v_fmac_f32_e32 v85, v84, v84
	v_add_f32_e32 v82, v89, v83
	v_add_f32_e32 v83, v91, v85
	v_add_f32_e32 v88, v82, v83
	global_store_dwordx4 v[86:87], v[72:75], off
	s_waitcnt vmcnt(13)
	v_mov_b32_e32 v76, v196
	v_mov_b32_e32 v77, v197
	v_mov_b32_e32 v78, v198
	v_mov_b32_e32 v79, v199
	v_lshlrev_b32_e32 v82, 16, v76
	v_and_b32_e32 v83, 0xffff0000, v76
	v_lshlrev_b32_e32 v76, 16, v77
	v_and_b32_e32 v77, 0xffff0000, v77
	v_lshlrev_b32_e32 v84, 16, v78
	v_and_b32_e32 v85, 0xffff0000, v78
	v_lshlrev_b32_e32 v78, 16, v79
	v_and_b32_e32 v79, 0xffff0000, v79
	v_pk_add_f32 v[70:71], v[70:71], v[76:77]
	v_pk_add_f32 v[68:69], v[68:69], v[82:83]
	v_pk_add_f32 v[76:77], v[66:67], v[78:79]
	v_pk_add_f32 v[78:79], v[64:65], v[84:85]
	v_mul_f32_e32 v64, v69, v69
	v_mul_f32_e32 v65, v71, v71
	v_mul_f32_e32 v66, v79, v79
	v_mul_f32_e32 v67, v77, v77
	v_fmac_f32_e32 v64, v68, v68
	v_fmac_f32_e32 v65, v70, v70
	v_fmac_f32_e32 v66, v78, v78
	v_fmac_f32_e32 v67, v76, v76
	v_add_f32_e32 v64, v64, v65
	v_add_f32_e32 v65, v66, v67
	v_add_f32_e32 v64, v64, v65
	v_add_f32_e32 v64, v88, v64
	ds_bpermute_b32 v65, v120, v64
	v_cvt_pk_bf16_f32 v66, v68, v69
	v_cvt_pk_bf16_f32 v67, v70, v71
	v_cvt_pk_bf16_f32 v68, v78, v79
	v_cvt_pk_bf16_f32 v69, v76, v77
	s_waitcnt lgkmcnt(0)
	v_add_f32_e32 v64, v64, v65
	ds_bpermute_b32 v65, v114, v64
	global_store_dwordx4 v[86:87], v[66:69], off offset:256
	s_and_saveexec_b64 s[52:53], s[2:3]
	s_cbranch_execz .LBB0_1076
	s_waitcnt lgkmcnt(0)
	v_add_f32_e32 v66, v64, v65
	s_lshl_b32 s18, s58, 2
	v_lshlrev_b64 v[64:65], 7, v[80:81]
	s_ashr_i32 s19, s18, 31
	v_lshl_add_u64 v[64:65], s[48:49], 0, v[64:65]
	v_lshl_add_u64 v[64:65], s[18:19], 2, v[64:65]
	s_lshl_b32 s18, s64, 2
	s_mov_b32 s19, s21
	v_lshl_add_u64 v[64:65], v[64:65], 0, s[18:19]
	global_store_dword v[64:65], v66, off
.LBB0_1076:
	s_or_b64 exec, exec, s[52:53]
	v_add_u32_e32 v64, 0x80, v146
	s_waitcnt lgkmcnt(0)
	v_ashrrev_i32_e32 v65, 31, v64
	v_lshlrev_b64 v[66:67], 12, v[64:65]
	v_lshl_add_u64 v[66:67], s[50:51], 0, v[66:67]
	v_lshl_add_u64 v[70:71], v[144:145], 1, v[66:67]
	s_waitcnt vmcnt(13)
	v_mov_b32_e32 v66, v200
	v_mov_b32_e32 v67, v201
	v_mov_b32_e32 v68, v202
	v_mov_b32_e32 v69, v203
	v_lshlrev_b32_e32 v72, 16, v66
	v_and_b32_e32 v73, 0xffff0000, v66
	v_lshlrev_b32_e32 v66, 16, v67
	v_and_b32_e32 v67, 0xffff0000, v67
	v_lshlrev_b32_e32 v74, 16, v68
	v_and_b32_e32 v75, 0xffff0000, v68
	v_lshlrev_b32_e32 v68, 16, v69
	v_and_b32_e32 v69, 0xffff0000, v69
	v_pk_add_f32 v[66:67], v[62:63], v[66:67]
	v_pk_add_f32 v[72:73], v[60:61], v[72:73]
	v_pk_add_f32 v[68:69], v[58:59], v[68:69]
	v_pk_add_f32 v[74:75], v[56:57], v[74:75]
	v_cvt_pk_bf16_f32 v56, v72, v73
	v_cvt_pk_bf16_f32 v57, v66, v67
	v_mul_f32_e32 v73, v73, v73
	v_cvt_pk_bf16_f32 v58, v74, v75
	v_cvt_pk_bf16_f32 v59, v68, v69
	v_mul_f32_e32 v67, v67, v67
	v_mul_f32_e32 v75, v75, v75
	v_mul_f32_e32 v69, v69, v69
	v_fmac_f32_e32 v73, v72, v72
	v_fmac_f32_e32 v67, v66, v66
	v_fmac_f32_e32 v75, v74, v74
	v_fmac_f32_e32 v69, v68, v68
	v_add_f32_e32 v66, v73, v67
	v_add_f32_e32 v67, v75, v69
	v_add_f32_e32 v72, v66, v67
	global_store_dwordx4 v[70:71], v[56:59], off
	s_waitcnt vmcnt(13)
	v_mov_b32_e32 v60, v204
	v_mov_b32_e32 v61, v205
	v_mov_b32_e32 v62, v206
	v_mov_b32_e32 v63, v207
	v_lshlrev_b32_e32 v66, 16, v60
	v_and_b32_e32 v67, 0xffff0000, v60
	v_lshlrev_b32_e32 v60, 16, v61
	v_and_b32_e32 v61, 0xffff0000, v61
	v_lshlrev_b32_e32 v68, 16, v62
	v_and_b32_e32 v69, 0xffff0000, v62
	v_lshlrev_b32_e32 v62, 16, v63
	v_and_b32_e32 v63, 0xffff0000, v63
	v_pk_add_f32 v[54:55], v[54:55], v[60:61]
	v_pk_add_f32 v[52:53], v[52:53], v[66:67]
	v_pk_add_f32 v[60:61], v[50:51], v[62:63]
	v_pk_add_f32 v[62:63], v[48:49], v[68:69]
	v_mul_f32_e32 v48, v53, v53
	v_mul_f32_e32 v49, v55, v55
	v_mul_f32_e32 v50, v63, v63
	v_mul_f32_e32 v51, v61, v61
	v_fmac_f32_e32 v48, v52, v52
	v_fmac_f32_e32 v49, v54, v54
	v_fmac_f32_e32 v50, v62, v62
	v_fmac_f32_e32 v51, v60, v60
	v_add_f32_e32 v48, v48, v49
	v_add_f32_e32 v49, v50, v51
	v_add_f32_e32 v48, v48, v49
	v_add_f32_e32 v48, v72, v48
	ds_bpermute_b32 v49, v120, v48
	v_cvt_pk_bf16_f32 v50, v52, v53
	v_cvt_pk_bf16_f32 v51, v54, v55
	v_cvt_pk_bf16_f32 v52, v62, v63
	v_cvt_pk_bf16_f32 v53, v60, v61
	s_waitcnt lgkmcnt(0)
	v_add_f32_e32 v48, v48, v49
	ds_bpermute_b32 v49, v114, v48
	global_store_dwordx4 v[70:71], v[50:53], off offset:256
	s_and_saveexec_b64 s[52:53], s[2:3]
	s_cbranch_execz .LBB0_1078
	s_waitcnt lgkmcnt(0)
	v_add_f32_e32 v50, v48, v49
	s_lshl_b32 s18, s58, 2
	v_lshlrev_b64 v[48:49], 7, v[64:65]
	s_ashr_i32 s19, s18, 31
	v_lshl_add_u64 v[48:49], s[48:49], 0, v[48:49]
	v_lshl_add_u64 v[48:49], s[18:19], 2, v[48:49]
	s_lshl_b32 s18, s64, 2
	s_mov_b32 s19, s21
	v_lshl_add_u64 v[48:49], v[48:49], 0, s[18:19]
	global_store_dword v[48:49], v50, off
; __device__ __forceinline__ unsigned cvt_pk_bf16(float lo, float hi) { unsigned r; asm volatile("v_cvt_pk_bf16_f32 %0, %1, %2" : "=v"(r) : "v"(lo), "v"(hi)); return r; }
; __device__ __forceinline__ float bf_lo(unsigned u) { return __uint_as_float(u << 16); }
; __device__ __forceinline__ float bf_hi(unsigned u) { return __uint_as_float(u & 0xffff0000u); }
;     __device__ __forceinline__ void operator()(const f32x4 (&acc)[2][2][4][2], const Unit& u, int wr, int wc, int fr, int fq) const {
;     ...
;         for (int ai = 0; ai < 2; ++ai)
; #pragma unroll
;             for (int m = 0; m < 4; ++m) { const int row = row0 + ai * HALF + m * 16; bf16_t* rowp = XB + (size_t)row * D + col0; float ss = 0.f;
; #pragma unroll
;                 for (int bj = 0; bj < 2; ++bj) { const u32x4 r = *(const u32x4*)(rowp + bj * HALF);
;                     const f32x4 o0 = (f32x4){bf_lo(r.x), bf_hi(r.x), bf_lo(r.y), bf_hi(r.y)} + acc[ai][bj][m][0] * alpha, o1 = (f32x4){bf_lo(r.z), bf_hi(r.z), bf_lo(r.w), bf_hi(r.w)} + acc[ai][bj][m][1] * alpha;
;                     ss += ((o0[0] * o0[0] + o0[1] * o0[1]) + (o0[2] * o0[2] + o0[3] * o0[3])) + ((o1[0] * o1[0] + o1[1] * o1[1]) + (o1[2] * o1[2] + o1[3] * o1[3]));
;                     u32x4 w; w.x = cvt_pk_bf16(o0[0], o0[1]); w.y = cvt_pk_bf16(o0[2], o0[3]); w.z = cvt_pk_bf16(o1[0], o1[1]); w.w = cvt_pk_bf16(o1[2], o1[3]);
;                     *(u32x4*)(rowp + bj * HALF) = w; }
;                 ss += __shfl_xor(ss, 16); ss += __shfl_xor(ss, 32);
;                 if (fq == 0) part[(size_t)row * NPART + u.pn * 4 + wc] = ss; }
.LBB0_1078:
	s_or_b64 exec, exec, s[52:53]
	v_add_u32_e32 v48, 0x90, v146
	s_waitcnt lgkmcnt(0)
	v_ashrrev_i32_e32 v49, 31, v48
	v_lshlrev_b64 v[50:51], 12, v[48:49]
	v_lshl_add_u64 v[50:51], s[50:51], 0, v[50:51]
	v_lshl_add_u64 v[54:55], v[144:145], 1, v[50:51]
	s_waitcnt vmcnt(13)
	v_mov_b32_e32 v50, v208
	v_mov_b32_e32 v51, v209
	v_mov_b32_e32 v52, v210
	v_mov_b32_e32 v53, v211
	v_lshlrev_b32_e32 v56, 16, v50
	v_and_b32_e32 v57, 0xffff0000, v50
	v_lshlrev_b32_e32 v50, 16, v51
	v_and_b32_e32 v51, 0xffff0000, v51
	v_lshlrev_b32_e32 v58, 16, v52
	v_and_b32_e32 v59, 0xffff0000, v52
	v_lshlrev_b32_e32 v52, 16, v53
	v_and_b32_e32 v53, 0xffff0000, v53
	v_pk_add_f32 v[50:51], v[46:47], v[50:51]
	v_pk_add_f32 v[56:57], v[44:45], v[56:57]
	v_pk_add_f32 v[52:53], v[42:43], v[52:53]
	v_pk_add_f32 v[58:59], v[40:41], v[58:59]
	v_cvt_pk_bf16_f32 v40, v56, v57
	v_cvt_pk_bf16_f32 v41, v50, v51
	v_mul_f32_e32 v57, v57, v57
	v_cvt_pk_bf16_f32 v42, v58, v59
	v_cvt_pk_bf16_f32 v43, v52, v53
	v_mul_f32_e32 v51, v51, v51
	v_mul_f32_e32 v59, v59, v59
	v_mul_f32_e32 v53, v53, v53
	v_fmac_f32_e32 v57, v56, v56
	v_fmac_f32_e32 v51, v50, v50
	v_fmac_f32_e32 v59, v58, v58
	v_fmac_f32_e32 v53, v52, v52
	v_add_f32_e32 v50, v57, v51
	v_add_f32_e32 v51, v59, v53
	v_add_f32_e32 v56, v50, v51
	global_store_dwordx4 v[54:55], v[40:43], off
	s_waitcnt vmcnt(13)
	v_mov_b32_e32 v44, v212
	v_mov_b32_e32 v45, v213
	v_mov_b32_e32 v46, v214
	v_mov_b32_e32 v47, v215
	v_lshlrev_b32_e32 v50, 16, v44
	v_and_b32_e32 v51, 0xffff0000, v44
	v_lshlrev_b32_e32 v44, 16, v45
	v_and_b32_e32 v45, 0xffff0000, v45
	v_lshlrev_b32_e32 v52, 16, v46
	v_and_b32_e32 v53, 0xffff0000, v46
	v_lshlrev_b32_e32 v46, 16, v47
	v_and_b32_e32 v47, 0xffff0000, v47
	v_pk_add_f32 v[38:39], v[38:39], v[44:45]
	v_pk_add_f32 v[36:37], v[36:37], v[50:51]
	v_pk_add_f32 v[44:45], v[34:35], v[46:47]
	v_pk_add_f32 v[46:47], v[32:33], v[52:53]
	v_mul_f32_e32 v32, v37, v37
	v_mul_f32_e32 v33, v39, v39
	v_mul_f32_e32 v34, v47, v47
	v_mul_f32_e32 v35, v45, v45
	v_fmac_f32_e32 v32, v36, v36
	v_fmac_f32_e32 v33, v38, v38
	v_fmac_f32_e32 v34, v46, v46
	v_fmac_f32_e32 v35, v44, v44
	v_add_f32_e32 v32, v32, v33
	v_add_f32_e32 v33, v34, v35
	v_add_f32_e32 v32, v32, v33
	v_add_f32_e32 v32, v56, v32
	ds_bpermute_b32 v33, v120, v32
	v_cvt_pk_bf16_f32 v34, v36, v37
	v_cvt_pk_bf16_f32 v35, v38, v39
	v_cvt_pk_bf16_f32 v36, v46, v47
	v_cvt_pk_bf16_f32 v37, v44, v45
	s_waitcnt lgkmcnt(0)
	v_add_f32_e32 v32, v32, v33
	ds_bpermute_b32 v33, v114, v32
	global_store_dwordx4 v[54:55], v[34:37], off offset:256
	s_and_saveexec_b64 s[52:53], s[2:3]
	s_cbranch_execz .LBB0_1080
	s_waitcnt lgkmcnt(0)
	v_add_f32_e32 v34, v32, v33
	s_lshl_b32 s18, s58, 2
	v_lshlrev_b64 v[32:33], 7, v[48:49]
	s_ashr_i32 s19, s18, 31
	v_lshl_add_u64 v[32:33], s[48:49], 0, v[32:33]
	v_lshl_add_u64 v[32:33], s[18:19], 2, v[32:33]
	s_lshl_b32 s18, s64, 2
	s_mov_b32 s19, s21
	v_lshl_add_u64 v[32:33], v[32:33], 0, s[18:19]
	global_store_dword v[32:33], v34, off
.LBB0_1080:
	s_or_b64 exec, exec, s[52:53]
	v_add_u32_e32 v32, 0xa0, v146
	s_waitcnt lgkmcnt(0)
	v_ashrrev_i32_e32 v33, 31, v32
	v_lshlrev_b64 v[34:35], 12, v[32:33]
	v_lshl_add_u64 v[34:35], s[50:51], 0, v[34:35]
	v_lshl_add_u64 v[38:39], v[144:145], 1, v[34:35]
	s_waitcnt vmcnt(13)
	v_mov_b32_e32 v34, v216
	v_mov_b32_e32 v35, v217
	v_mov_b32_e32 v36, v218
	v_mov_b32_e32 v37, v219
	v_lshlrev_b32_e32 v40, 16, v34
	v_and_b32_e32 v41, 0xffff0000, v34
	v_lshlrev_b32_e32 v34, 16, v35
	v_and_b32_e32 v35, 0xffff0000, v35
	v_lshlrev_b32_e32 v42, 16, v36
	v_and_b32_e32 v43, 0xffff0000, v36
	v_lshlrev_b32_e32 v36, 16, v37
	v_and_b32_e32 v37, 0xffff0000, v37
	v_pk_add_f32 v[34:35], v[30:31], v[34:35]
	v_pk_add_f32 v[40:41], v[28:29], v[40:41]
	v_pk_add_f32 v[36:37], v[26:27], v[36:37]
	v_pk_add_f32 v[42:43], v[24:25], v[42:43]
	v_cvt_pk_bf16_f32 v24, v40, v41
	v_cvt_pk_bf16_f32 v25, v34, v35
	v_mul_f32_e32 v41, v41, v41
	v_cvt_pk_bf16_f32 v26, v42, v43
	v_cvt_pk_bf16_f32 v27, v36, v37
	v_mul_f32_e32 v35, v35, v35
	v_mul_f32_e32 v43, v43, v43
	v_mul_f32_e32 v37, v37, v37
	v_fmac_f32_e32 v41, v40, v40
	v_fmac_f32_e32 v35, v34, v34
	v_fmac_f32_e32 v43, v42, v42
	v_fmac_f32_e32 v37, v36, v36
	v_add_f32_e32 v34, v41, v35
	v_add_f32_e32 v35, v43, v37
	v_add_f32_e32 v40, v34, v35
	global_store_dwordx4 v[38:39], v[24:27], off
	s_waitcnt vmcnt(13)
	v_mov_b32_e32 v28, v222
	v_mov_b32_e32 v29, v223
	v_mov_b32_e32 v30, v224
	v_mov_b32_e32 v31, v225
	v_lshlrev_b32_e32 v34, 16, v28
	v_and_b32_e32 v35, 0xffff0000, v28
	v_lshlrev_b32_e32 v28, 16, v29
	v_and_b32_e32 v29, 0xffff0000, v29
	v_lshlrev_b32_e32 v36, 16, v30
	v_and_b32_e32 v37, 0xffff0000, v30
	v_lshlrev_b32_e32 v30, 16, v31
	v_and_b32_e32 v31, 0xffff0000, v31
	v_pk_add_f32 v[22:23], v[22:23], v[28:29]
	v_pk_add_f32 v[20:21], v[20:21], v[34:35]
	v_pk_add_f32 v[28:29], v[18:19], v[30:31]
	v_pk_add_f32 v[30:31], v[16:17], v[36:37]
	v_mul_f32_e32 v16, v21, v21
	v_mul_f32_e32 v17, v23, v23
	v_mul_f32_e32 v18, v31, v31
	v_mul_f32_e32 v19, v29, v29
	v_fmac_f32_e32 v16, v20, v20
	v_fmac_f32_e32 v17, v22, v22
	v_fmac_f32_e32 v18, v30, v30
	v_fmac_f32_e32 v19, v28, v28
	v_add_f32_e32 v16, v16, v17
	v_add_f32_e32 v17, v18, v19
	v_add_f32_e32 v16, v16, v17
	v_add_f32_e32 v16, v40, v16
	ds_bpermute_b32 v17, v120, v16
	v_cvt_pk_bf16_f32 v18, v20, v21
	v_cvt_pk_bf16_f32 v19, v22, v23
	v_cvt_pk_bf16_f32 v20, v30, v31
	v_cvt_pk_bf16_f32 v21, v28, v29
	s_waitcnt lgkmcnt(0)
	v_add_f32_e32 v16, v16, v17
	ds_bpermute_b32 v17, v114, v16
	global_store_dwordx4 v[38:39], v[18:21], off offset:256
	s_and_saveexec_b64 s[52:53], s[2:3]
	s_cbranch_execz .LBB0_1082
	s_waitcnt lgkmcnt(0)
	v_add_f32_e32 v18, v16, v17
	s_lshl_b32 s18, s58, 2
	v_lshlrev_b64 v[16:17], 7, v[32:33]
	s_ashr_i32 s19, s18, 31
	v_lshl_add_u64 v[16:17], s[48:49], 0, v[16:17]
	v_lshl_add_u64 v[16:17], s[18:19], 2, v[16:17]
	s_lshl_b32 s18, s64, 2
	s_mov_b32 s19, s21
	v_lshl_add_u64 v[16:17], v[16:17], 0, s[18:19]
	global_store_dword v[16:17], v18, off
